# v22 + RWKV scan loop: the two adjacent counted lgkmcnt waits per step merged into one (30 s_waitcnt removed per 32-step chunk); bit-identical
# baseline (speedup 1.0000x reference)
; __device__ __forceinline__ void scan_phase(const Args& a, int li, LAS unsigned char* lds) {
;     ...
;                 StepVec V0, V1, V2; SC_LOADV(V0, 0); SC_LOADV(V1, 1); float yk = 0.f, qprev = 0.f;
; #pragma unroll
;                 for (int t = 0; t < 32; ++t) {
;                     switch (t % 3) { case 0: SC_STEPF(V0, V2, (t + 2) & 31, (t + 7) & 7); break; case 1: SC_STEPF(V1, V0, (t + 2) & 31, (t + 7) & 7); break; default: SC_STEPF(V2, V1, (t + 2) & 31, (t + 7) & 7); break; }
.LBB0_532:
	s_and_b32 s4, s1, 1
	s_mul_i32 s5, s4, 0xc000
	s_add_i32 s5, s5, 0
	v_add_u32_e32 v8, s5, v87
	s_add_i32 s5, s5, s0
	v_add_u32_e32 v9, s5, v89
	ds_read_b128 v[12:15], v8 offset:33024
	ds_read_b128 v[16:19], v8 offset:33040
	ds_read_b128 v[20:23], v8 offset:8448
	ds_read_b128 v[24:27], v8 offset:8464
	ds_read_b128 v[28:31], v8 offset:41216
	ds_read_b128 v[32:35], v8 offset:41232
	ds_read_b128 v[36:39], v8 offset:16640
	ds_read_b128 v[40:43], v8 offset:16656
	ds_read_b128 v[44:47], v8 offset:256
	ds_read_b128 v[48:51], v8 offset:272
	ds_read2st64_b32 v[126:127], v9 offset0:96 offset1:97
	ds_read_b128 v[52:55], v8
	ds_read_b128 v[56:59], v8 offset:16
	ds_read_b128 v[60:63], v8 offset:16400
	ds_read_b128 v[64:67], v8 offset:16384
	ds_read_b128 v[68:71], v8 offset:40976
	ds_read_b128 v[72:75], v8 offset:40960
	ds_read_b128 v[102:105], v8 offset:32784
	ds_read_b128 v[106:109], v8 offset:32768
	ds_read_b128 v[110:113], v8 offset:8208
	ds_read_b128 v[114:117], v8 offset:8192
	s_lshl_b32 s4, s4, 12
	v_add_u32_e32 v10, s4, v97
	s_waitcnt lgkmcnt(2)
	v_pk_mul_f32 v[106:107], v[0:1], v[106:107]
	v_pk_mul_f32 v[128:129], v[126:127], v[64:65] op_sel_hi:[0,1]
	v_mov_b32_dpp v11, v169 quad_perm:[1,0,3,2] row_mask:0xf bank_mask:0xf bound_ctrl:1
	v_add_f32_e32 v11, 0, v11
	v_pk_fma_f32 v[64:65], v[2:3], v[108:109], v[106:107]
	v_pk_mul_f32 v[130:131], v[126:127], v[66:67] op_sel_hi:[0,1]
	v_add_f32_dpp v11, v11, v11 quad_perm:[2,3,0,1] row_mask:0xf bank_mask:0xf bound_ctrl:1
	v_pk_fma_f32 v[64:65], v[4:5], v[102:103], v[64:65]
	v_pk_mul_f32 v[132:133], v[126:127], v[60:61] op_sel_hi:[0,1]
	v_add_f32_dpp v11, v11, v11 row_half_mirror row_mask:0xf bank_mask:0xf bound_ctrl:1
	v_pk_fma_f32 v[60:61], v[6:7], v[104:105], v[64:65]
	v_pk_mul_f32 v[160:161], v[126:127], v[62:63] op_sel_hi:[0,1]
	v_cndmask_b32_e64 v11, 0, v11, s[38:39]
	v_add_f32_e32 v101, v60, v61
	ds_read_b128 v[60:63], v8 offset:33280
	ds_read_b128 v[64:67], v8 offset:33296
	v_add_f32_dpp v101, v101, v101 quad_perm:[1,0,3,2] row_mask:0xf bank_mask:0xf bound_ctrl:1
	ds_read_b128 v[102:105], v8 offset:8704
	ds_read_b128 v[106:109], v8 offset:8720
	v_add_f32_dpp v101, v101, v101 quad_perm:[2,3,0,1] row_mask:0xf bank_mask:0xf bound_ctrl:1
	ds_read_b128 v[118:121], v8 offset:41472
	ds_read_b128 v[122:125], v8 offset:41488
	v_add_f32_dpp v126, v101, v101 row_half_mirror row_mask:0xf bank_mask:0xf bound_ctrl:1
	v_pk_fma_f32 v[72:73], v[126:127], v[72:73], v[128:129] op_sel_hi:[0,1,1] neg_lo:[1,0,0] neg_hi:[1,0,0]
	v_pk_fma_f32 v[74:75], v[126:127], v[74:75], v[130:131] op_sel_hi:[0,1,1] neg_lo:[1,0,0] neg_hi:[1,0,0]
	v_pk_fma_f32 v[68:69], v[126:127], v[68:69], v[132:133] op_sel_hi:[0,1,1] neg_lo:[1,0,0] neg_hi:[1,0,0]
	v_pk_fma_f32 v[70:71], v[126:127], v[70:71], v[160:161] op_sel_hi:[0,1,1] neg_lo:[1,0,0] neg_hi:[1,0,0]
	s_waitcnt lgkmcnt(6)
	v_pk_fma_f32 v[114:115], v[0:1], v[114:115], v[72:73]
	v_pk_fma_f32 v[116:117], v[2:3], v[116:117], v[74:75]
	v_pk_fma_f32 v[110:111], v[4:5], v[110:111], v[68:69]
	v_pk_fma_f32 v[112:113], v[6:7], v[112:113], v[70:71]
	v_pk_mul_f32 v[4:5], v[52:53], v[114:115]
	ds_read_b128 v[0:3], v8 offset:16896
	v_pk_fma_f32 v[52:53], v[116:117], v[54:55], v[4:5]
	ds_read_b128 v[4:7], v8 offset:16912
	v_pk_fma_f32 v[56:57], v[110:111], v[56:57], v[52:53]
	ds_read_b128 v[52:55], v8 offset:512
	v_pk_fma_f32 v[68:69], v[112:113], v[58:59], v[56:57]
	ds_read_b128 v[56:59], v8 offset:528
	ds_read_b32 v126, v9 offset:25088
	v_add_f32_e32 v69, v68, v69
	v_mov_b32_e32 v68, v127
	v_pk_mul_f32 v[12:13], v[12:13], v[114:115]
	v_pk_mul_f32 v[128:129], v[36:37], v[68:69] op_sel_hi:[1,0]
	v_add_f32_dpp v36, v69, v69 quad_perm:[1,0,3,2] row_mask:0xf bank_mask:0xf bound_ctrl:1
	v_pk_fma_f32 v[12:13], v[116:117], v[14:15], v[12:13]
	v_pk_mul_f32 v[130:131], v[38:39], v[68:69] op_sel_hi:[1,0]
	v_add_f32_dpp v14, v36, v36 quad_perm:[2,3,0,1] row_mask:0xf bank_mask:0xf bound_ctrl:1
	v_pk_fma_f32 v[12:13], v[110:111], v[16:17], v[12:13]
	v_pk_mul_f32 v[132:133], v[40:41], v[68:69] op_sel_hi:[1,0]
	v_add_f32_dpp v14, v14, v14 row_half_mirror row_mask:0xf bank_mask:0xf bound_ctrl:1
	v_pk_fma_f32 v[12:13], v[112:113], v[18:19], v[12:13]
	v_pk_mul_f32 v[160:161], v[42:43], v[68:69] op_sel_hi:[1,0]
	v_cndmask_b32_e64 v11, v11, v14, s[48:49]
	v_add_f32_e32 v36, v12, v13
	ds_read_b128 v[12:15], v8 offset:33536
	ds_read_b128 v[16:19], v8 offset:33552
	v_add_f32_dpp v68, v36, v36 quad_perm:[1,0,3,2] row_mask:0xf bank_mask:0xf bound_ctrl:1
	ds_read_b128 v[36:39], v8 offset:8960
	ds_read_b128 v[40:43], v8 offset:8976
	v_add_f32_dpp v101, v68, v68 quad_perm:[2,3,0,1] row_mask:0xf bank_mask:0xf bound_ctrl:1
	ds_read_b128 v[68:71], v8 offset:41728
	ds_read_b128 v[72:75], v8 offset:41744
	v_add_f32_dpp v162, v101, v101 row_half_mirror row_mask:0xf bank_mask:0xf bound_ctrl:1
	v_pk_fma_f32 v[28:29], v[162:163], v[28:29], v[128:129] op_sel_hi:[0,1,1] neg_lo:[1,0,0] neg_hi:[1,0,0]
	v_pk_fma_f32 v[30:31], v[162:163], v[30:31], v[130:131] op_sel_hi:[0,1,1] neg_lo:[1,0,0] neg_hi:[1,0,0]
	v_pk_fma_f32 v[32:33], v[162:163], v[32:33], v[132:133] op_sel_hi:[0,1,1] neg_lo:[1,0,0] neg_hi:[1,0,0]
	v_pk_fma_f32 v[34:35], v[162:163], v[34:35], v[160:161] op_sel_hi:[0,1,1] neg_lo:[1,0,0] neg_hi:[1,0,0]
	v_pk_fma_f32 v[114:115], v[114:115], v[20:21], v[28:29]
	v_pk_fma_f32 v[116:117], v[116:117], v[22:23], v[30:31]
	v_pk_fma_f32 v[110:111], v[110:111], v[24:25], v[32:33]
	v_pk_fma_f32 v[112:113], v[112:113], v[26:27], v[34:35]
	v_pk_mul_f32 v[24:25], v[44:45], v[114:115]
	ds_read_b128 v[20:23], v8 offset:17152
	v_pk_fma_f32 v[28:29], v[116:117], v[46:47], v[24:25]
	ds_read_b128 v[24:27], v8 offset:17168
	v_pk_fma_f32 v[32:33], v[110:111], v[48:49], v[28:29]
	ds_read_b128 v[28:31], v8 offset:768
	v_pk_fma_f32 v[44:45], v[112:113], v[50:51], v[32:33]
	ds_read_b128 v[32:35], v8 offset:784
	ds_read_b32 v128, v9 offset:25344
	v_add_f32_e32 v46, v44, v45
	s_waitcnt lgkmcnt(11)
; __device__ __forceinline__ void scan_phase(const Args& a, int li, LAS unsigned char* lds) {
;     ...
;                 StepVec V0, V1, V2; SC_LOADV(V0, 0); SC_LOADV(V1, 1); float yk = 0.f, qprev = 0.f;
; #pragma unroll
;                 for (int t = 0; t < 32; ++t) {
;                     switch (t % 3) { case 0: SC_STEPF(V0, V2, (t + 2) & 31, (t + 7) & 7); break; case 1: SC_STEPF(V1, V0, (t + 2) & 31, (t + 7) & 7); break; default: SC_STEPF(V2, V1, (t + 2) & 31, (t + 7) & 7); break; }
	v_pk_mul_f32 v[44:45], v[60:61], v[114:115]
	v_pk_mul_f32 v[130:131], v[0:1], v[126:127] op_sel_hi:[1,0]
	v_add_f32_dpp v46, v46, v46 quad_perm:[1,0,3,2] row_mask:0xf bank_mask:0xf bound_ctrl:1
	v_pk_fma_f32 v[0:1], v[116:117], v[62:63], v[44:45]
	v_pk_mul_f32 v[132:133], v[2:3], v[126:127] op_sel_hi:[1,0]
	v_add_f32_dpp v2, v46, v46 quad_perm:[2,3,0,1] row_mask:0xf bank_mask:0xf bound_ctrl:1
	v_pk_fma_f32 v[0:1], v[110:111], v[64:65], v[0:1]
	v_pk_mul_f32 v[160:161], v[4:5], v[126:127] op_sel_hi:[1,0]
	v_add_f32_dpp v2, v2, v2 row_half_mirror row_mask:0xf bank_mask:0xf bound_ctrl:1
	v_pk_fma_f32 v[0:1], v[112:113], v[66:67], v[0:1]
	v_pk_mul_f32 v[126:127], v[6:7], v[126:127] op_sel_hi:[1,0]
	v_cndmask_b32_e64 v11, v11, v2, s[50:51]
	v_add_f32_e32 v44, v0, v1
	ds_read_b128 v[0:3], v8 offset:33792
	ds_read_b128 v[4:7], v8 offset:33808
	v_add_f32_dpp v60, v44, v44 quad_perm:[1,0,3,2] row_mask:0xf bank_mask:0xf bound_ctrl:1
	ds_read_b128 v[44:47], v8 offset:9216
	ds_read_b128 v[48:51], v8 offset:9232
	v_add_f32_dpp v101, v60, v60 quad_perm:[2,3,0,1] row_mask:0xf bank_mask:0xf bound_ctrl:1
	ds_read_b128 v[60:63], v8 offset:41984
	ds_read_b128 v[64:67], v8 offset:42000
	v_add_f32_dpp v162, v101, v101 row_half_mirror row_mask:0xf bank_mask:0xf bound_ctrl:1
	v_pk_fma_f32 v[118:119], v[162:163], v[118:119], v[130:131] op_sel_hi:[0,1,1] neg_lo:[1,0,0] neg_hi:[1,0,0]
	v_pk_fma_f32 v[120:121], v[162:163], v[120:121], v[132:133] op_sel_hi:[0,1,1] neg_lo:[1,0,0] neg_hi:[1,0,0]
	v_pk_fma_f32 v[122:123], v[162:163], v[122:123], v[160:161] op_sel_hi:[0,1,1] neg_lo:[1,0,0] neg_hi:[1,0,0]
	v_pk_fma_f32 v[124:125], v[162:163], v[124:125], v[126:127] op_sel_hi:[0,1,1] neg_lo:[1,0,0] neg_hi:[1,0,0]
	v_pk_fma_f32 v[118:119], v[114:115], v[102:103], v[118:119]
	v_pk_fma_f32 v[120:121], v[116:117], v[104:105], v[120:121]
	v_pk_fma_f32 v[122:123], v[110:111], v[106:107], v[122:123]
	v_pk_fma_f32 v[124:125], v[112:113], v[108:109], v[124:125]
	v_pk_mul_f32 v[52:53], v[52:53], v[118:119]
	ds_read_b128 v[102:105], v8 offset:17408
	v_pk_fma_f32 v[106:107], v[120:121], v[54:55], v[52:53]
	ds_read_b128 v[52:55], v8 offset:17424
	v_pk_fma_f32 v[56:57], v[122:123], v[56:57], v[106:107]
	ds_read_b128 v[106:109], v8 offset:1024
	v_pk_fma_f32 v[110:111], v[124:125], v[58:59], v[56:57]
	ds_read_b128 v[56:59], v8 offset:1040
	ds_read_b32 v126, v9 offset:25600
	v_add_f32_e32 v101, v110, v111
	s_waitcnt lgkmcnt(11)
	v_pk_mul_f32 v[12:13], v[12:13], v[118:119]
	v_pk_mul_f32 v[130:131], v[20:21], v[128:129] op_sel_hi:[1,0]
	v_add_f32_dpp v20, v101, v101 quad_perm:[1,0,3,2] row_mask:0xf bank_mask:0xf bound_ctrl:1
	v_pk_fma_f32 v[12:13], v[120:121], v[14:15], v[12:13]
	v_pk_mul_f32 v[132:133], v[22:23], v[128:129] op_sel_hi:[1,0]
	v_add_f32_dpp v14, v20, v20 quad_perm:[2,3,0,1] row_mask:0xf bank_mask:0xf bound_ctrl:1
	v_pk_fma_f32 v[12:13], v[122:123], v[16:17], v[12:13]
	v_pk_mul_f32 v[160:161], v[24:25], v[128:129] op_sel_hi:[1,0]
	v_add_f32_dpp v14, v14, v14 row_half_mirror row_mask:0xf bank_mask:0xf bound_ctrl:1
	v_pk_fma_f32 v[12:13], v[124:125], v[18:19], v[12:13]
	v_pk_mul_f32 v[128:129], v[26:27], v[128:129] op_sel_hi:[1,0]
	v_cndmask_b32_e64 v11, v11, v14, s[52:53]
	v_add_f32_e32 v20, v12, v13
	ds_read_b128 v[12:15], v8 offset:34048
	ds_read_b128 v[16:19], v8 offset:34064
	v_add_f32_dpp v101, v20, v20 quad_perm:[1,0,3,2] row_mask:0xf bank_mask:0xf bound_ctrl:1
	ds_read_b128 v[20:23], v8 offset:9472
	ds_read_b128 v[24:27], v8 offset:9488
	v_add_f32_dpp v101, v101, v101 quad_perm:[2,3,0,1] row_mask:0xf bank_mask:0xf bound_ctrl:1
	ds_read_b128 v[110:113], v8 offset:42240
	ds_read_b128 v[114:117], v8 offset:42256
	v_add_f32_dpp v162, v101, v101 row_half_mirror row_mask:0xf bank_mask:0xf bound_ctrl:1
	v_pk_fma_f32 v[68:69], v[162:163], v[68:69], v[130:131] op_sel_hi:[0,1,1] neg_lo:[1,0,0] neg_hi:[1,0,0]
	v_pk_fma_f32 v[70:71], v[162:163], v[70:71], v[132:133] op_sel_hi:[0,1,1] neg_lo:[1,0,0] neg_hi:[1,0,0]
	v_pk_fma_f32 v[72:73], v[162:163], v[72:73], v[160:161] op_sel_hi:[0,1,1] neg_lo:[1,0,0] neg_hi:[1,0,0]
	v_pk_fma_f32 v[74:75], v[162:163], v[74:75], v[128:129] op_sel_hi:[0,1,1] neg_lo:[1,0,0] neg_hi:[1,0,0]
	v_pk_fma_f32 v[118:119], v[118:119], v[36:37], v[68:69]
	v_pk_fma_f32 v[120:121], v[120:121], v[38:39], v[70:71]
	v_pk_fma_f32 v[122:123], v[122:123], v[40:41], v[72:73]
	v_pk_fma_f32 v[124:125], v[124:125], v[42:43], v[74:75]
	v_pk_mul_f32 v[28:29], v[28:29], v[118:119]
	ds_read_b128 v[36:39], v8 offset:17664
	v_pk_fma_f32 v[40:41], v[120:121], v[30:31], v[28:29]
	ds_read_b128 v[28:31], v8 offset:17680
	v_pk_fma_f32 v[32:33], v[122:123], v[32:33], v[40:41]
	ds_read_b128 v[40:43], v8 offset:1280
	v_pk_fma_f32 v[68:69], v[124:125], v[34:35], v[32:33]
	ds_read_b128 v[32:35], v8 offset:1296
	ds_read_b32 v128, v9 offset:25856
	v_add_f32_e32 v68, v68, v69
	s_waitcnt lgkmcnt(11)
; __device__ __forceinline__ void scan_phase(const Args& a, int li, LAS unsigned char* lds) {
;     ...
;                 StepVec V0, V1, V2; SC_LOADV(V0, 0); SC_LOADV(V1, 1); float yk = 0.f, qprev = 0.f;
; #pragma unroll
;                 for (int t = 0; t < 32; ++t) {
;                     switch (t % 3) { case 0: SC_STEPF(V0, V2, (t + 2) & 31, (t + 7) & 7); break; case 1: SC_STEPF(V1, V0, (t + 2) & 31, (t + 7) & 7); break; default: SC_STEPF(V2, V1, (t + 2) & 31, (t + 7) & 7); break; }
	v_pk_mul_f32 v[0:1], v[0:1], v[118:119]
	v_pk_mul_f32 v[130:131], v[102:103], v[126:127] op_sel_hi:[1,0]
	v_add_f32_dpp v68, v68, v68 quad_perm:[1,0,3,2] row_mask:0xf bank_mask:0xf bound_ctrl:1
	v_pk_fma_f32 v[0:1], v[120:121], v[2:3], v[0:1]
	v_pk_mul_f32 v[132:133], v[104:105], v[126:127] op_sel_hi:[1,0]
	v_add_f32_dpp v2, v68, v68 quad_perm:[2,3,0,1] row_mask:0xf bank_mask:0xf bound_ctrl:1
	v_pk_fma_f32 v[0:1], v[122:123], v[4:5], v[0:1]
	v_pk_mul_f32 v[160:161], v[52:53], v[126:127] op_sel_hi:[1,0]
	v_add_f32_dpp v2, v2, v2 row_half_mirror row_mask:0xf bank_mask:0xf bound_ctrl:1
	v_pk_fma_f32 v[0:1], v[124:125], v[6:7], v[0:1]
	v_pk_mul_f32 v[126:127], v[54:55], v[126:127] op_sel_hi:[1,0]
	v_cndmask_b32_e64 v11, v11, v2, s[54:55]
	v_add_f32_e32 v52, v0, v1
	ds_read_b128 v[0:3], v8 offset:34304
	ds_read_b128 v[4:7], v8 offset:34320
	v_add_f32_dpp v72, v52, v52 quad_perm:[1,0,3,2] row_mask:0xf bank_mask:0xf bound_ctrl:1
	ds_read_b128 v[52:55], v8 offset:9728
	ds_read_b128 v[68:71], v8 offset:9744
	v_add_f32_dpp v101, v72, v72 quad_perm:[2,3,0,1] row_mask:0xf bank_mask:0xf bound_ctrl:1
	ds_read_b128 v[72:75], v8 offset:42496
	ds_read_b128 v[102:105], v8 offset:42512
	v_add_f32_dpp v162, v101, v101 row_half_mirror row_mask:0xf bank_mask:0xf bound_ctrl:1
	v_pk_fma_f32 v[60:61], v[162:163], v[60:61], v[130:131] op_sel_hi:[0,1,1] neg_lo:[1,0,0] neg_hi:[1,0,0]
	v_pk_fma_f32 v[62:63], v[162:163], v[62:63], v[132:133] op_sel_hi:[0,1,1] neg_lo:[1,0,0] neg_hi:[1,0,0]
	v_pk_fma_f32 v[64:65], v[162:163], v[64:65], v[160:161] op_sel_hi:[0,1,1] neg_lo:[1,0,0] neg_hi:[1,0,0]
	v_pk_fma_f32 v[66:67], v[162:163], v[66:67], v[126:127] op_sel_hi:[0,1,1] neg_lo:[1,0,0] neg_hi:[1,0,0]
	v_pk_fma_f32 v[118:119], v[118:119], v[44:45], v[60:61]
	v_pk_fma_f32 v[120:121], v[120:121], v[46:47], v[62:63]
	v_pk_fma_f32 v[122:123], v[122:123], v[48:49], v[64:65]
	v_pk_fma_f32 v[124:125], v[124:125], v[50:51], v[66:67]
	v_pk_mul_f32 v[48:49], v[106:107], v[118:119]
	ds_read_b128 v[44:47], v8 offset:17920
	v_pk_fma_f32 v[60:61], v[120:121], v[108:109], v[48:49]
	ds_read_b128 v[48:51], v8 offset:17936
	v_pk_fma_f32 v[56:57], v[122:123], v[56:57], v[60:61]
	ds_read_b128 v[60:63], v8 offset:1536
	v_pk_fma_f32 v[64:65], v[124:125], v[58:59], v[56:57]
	ds_read_b128 v[56:59], v8 offset:1552
	ds_read_b32 v126, v9 offset:26112
	v_add_f32_e32 v64, v64, v65
	s_waitcnt lgkmcnt(11)
	v_pk_mul_f32 v[12:13], v[12:13], v[118:119]
	v_pk_mul_f32 v[130:131], v[36:37], v[128:129] op_sel_hi:[1,0]
	v_add_f32_dpp v36, v64, v64 quad_perm:[1,0,3,2] row_mask:0xf bank_mask:0xf bound_ctrl:1
	v_pk_fma_f32 v[12:13], v[120:121], v[14:15], v[12:13]
	v_pk_mul_f32 v[132:133], v[38:39], v[128:129] op_sel_hi:[1,0]
	v_add_f32_dpp v14, v36, v36 quad_perm:[2,3,0,1] row_mask:0xf bank_mask:0xf bound_ctrl:1
	v_pk_fma_f32 v[12:13], v[122:123], v[16:17], v[12:13]
	v_pk_mul_f32 v[160:161], v[28:29], v[128:129] op_sel_hi:[1,0]
	v_add_f32_dpp v14, v14, v14 row_half_mirror row_mask:0xf bank_mask:0xf bound_ctrl:1
	v_pk_fma_f32 v[12:13], v[124:125], v[18:19], v[12:13]
	v_pk_mul_f32 v[128:129], v[30:31], v[128:129] op_sel_hi:[1,0]
	v_cndmask_b32_e64 v11, v11, v14, s[56:57]
	v_add_f32_e32 v28, v12, v13
	ds_read_b128 v[12:15], v8 offset:34560
	ds_read_b128 v[16:19], v8 offset:34576
	v_add_f32_dpp v64, v28, v28 quad_perm:[1,0,3,2] row_mask:0xf bank_mask:0xf bound_ctrl:1
	ds_read_b128 v[28:31], v8 offset:9984
	ds_read_b128 v[36:39], v8 offset:10000
	v_add_f32_dpp v101, v64, v64 quad_perm:[2,3,0,1] row_mask:0xf bank_mask:0xf bound_ctrl:1
	ds_read_b128 v[64:67], v8 offset:42752
	ds_read_b128 v[106:109], v8 offset:42768
	v_add_f32_dpp v162, v101, v101 row_half_mirror row_mask:0xf bank_mask:0xf bound_ctrl:1
	v_pk_fma_f32 v[110:111], v[162:163], v[110:111], v[130:131] op_sel_hi:[0,1,1] neg_lo:[1,0,0] neg_hi:[1,0,0]
	v_pk_fma_f32 v[112:113], v[162:163], v[112:113], v[132:133] op_sel_hi:[0,1,1] neg_lo:[1,0,0] neg_hi:[1,0,0]
	v_pk_fma_f32 v[114:115], v[162:163], v[114:115], v[160:161] op_sel_hi:[0,1,1] neg_lo:[1,0,0] neg_hi:[1,0,0]
	v_pk_fma_f32 v[116:117], v[162:163], v[116:117], v[128:129] op_sel_hi:[0,1,1] neg_lo:[1,0,0] neg_hi:[1,0,0]
	v_pk_fma_f32 v[118:119], v[118:119], v[20:21], v[110:111]
	v_pk_fma_f32 v[120:121], v[120:121], v[22:23], v[112:113]
	v_pk_fma_f32 v[122:123], v[122:123], v[24:25], v[114:115]
	v_pk_fma_f32 v[124:125], v[124:125], v[26:27], v[116:117]
	v_pk_mul_f32 v[24:25], v[40:41], v[118:119]
	ds_read_b128 v[20:23], v8 offset:18176
	v_pk_fma_f32 v[40:41], v[120:121], v[42:43], v[24:25]
	ds_read_b128 v[24:27], v8 offset:18192
	v_pk_fma_f32 v[32:33], v[122:123], v[32:33], v[40:41]
	ds_read_b128 v[40:43], v8 offset:1792
	v_pk_fma_f32 v[110:111], v[124:125], v[34:35], v[32:33]
	ds_read_b128 v[32:35], v8 offset:1808
	ds_read_b32 v128, v9 offset:26368
	v_add_f32_e32 v101, v110, v111
	s_waitcnt lgkmcnt(11)
; __device__ __forceinline__ void scan_phase(const Args& a, int li, LAS unsigned char* lds) {
;     ...
;                 StepVec V0, V1, V2; SC_LOADV(V0, 0); SC_LOADV(V1, 1); float yk = 0.f, qprev = 0.f;
; #pragma unroll
;                 for (int t = 0; t < 32; ++t) {
;                     switch (t % 3) { case 0: SC_STEPF(V0, V2, (t + 2) & 31, (t + 7) & 7); break; case 1: SC_STEPF(V1, V0, (t + 2) & 31, (t + 7) & 7); break; default: SC_STEPF(V2, V1, (t + 2) & 31, (t + 7) & 7); break; }
	v_pk_mul_f32 v[0:1], v[0:1], v[118:119]
	v_pk_mul_f32 v[130:131], v[44:45], v[126:127] op_sel_hi:[1,0]
	v_add_f32_dpp v44, v101, v101 quad_perm:[1,0,3,2] row_mask:0xf bank_mask:0xf bound_ctrl:1
	v_pk_fma_f32 v[0:1], v[120:121], v[2:3], v[0:1]
	v_pk_mul_f32 v[132:133], v[46:47], v[126:127] op_sel_hi:[1,0]
	v_add_f32_dpp v2, v44, v44 quad_perm:[2,3,0,1] row_mask:0xf bank_mask:0xf bound_ctrl:1
	v_pk_fma_f32 v[0:1], v[122:123], v[4:5], v[0:1]
	v_pk_mul_f32 v[160:161], v[48:49], v[126:127] op_sel_hi:[1,0]
	v_add_f32_dpp v2, v2, v2 row_half_mirror row_mask:0xf bank_mask:0xf bound_ctrl:1
	v_pk_fma_f32 v[0:1], v[124:125], v[6:7], v[0:1]
	v_pk_mul_f32 v[126:127], v[50:51], v[126:127] op_sel_hi:[1,0]
	v_cndmask_b32_e64 v11, v11, v2, s[58:59]
	v_add_f32_e32 v44, v0, v1
	ds_read_b128 v[0:3], v8 offset:34816
	ds_read_b128 v[4:7], v8 offset:34832
	v_add_f32_dpp v101, v44, v44 quad_perm:[1,0,3,2] row_mask:0xf bank_mask:0xf bound_ctrl:1
	ds_read_b128 v[44:47], v8 offset:10240
	ds_read_b128 v[48:51], v8 offset:10256
	v_add_f32_dpp v101, v101, v101 quad_perm:[2,3,0,1] row_mask:0xf bank_mask:0xf bound_ctrl:1
	ds_read_b128 v[110:113], v8 offset:43008
	ds_read_b128 v[114:117], v8 offset:43024
	v_add_f32_dpp v162, v101, v101 row_half_mirror row_mask:0xf bank_mask:0xf bound_ctrl:1
	v_pk_fma_f32 v[72:73], v[162:163], v[72:73], v[130:131] op_sel_hi:[0,1,1] neg_lo:[1,0,0] neg_hi:[1,0,0]
	v_pk_fma_f32 v[74:75], v[162:163], v[74:75], v[132:133] op_sel_hi:[0,1,1] neg_lo:[1,0,0] neg_hi:[1,0,0]
	v_pk_fma_f32 v[102:103], v[162:163], v[102:103], v[160:161] op_sel_hi:[0,1,1] neg_lo:[1,0,0] neg_hi:[1,0,0]
	v_pk_fma_f32 v[104:105], v[162:163], v[104:105], v[126:127] op_sel_hi:[0,1,1] neg_lo:[1,0,0] neg_hi:[1,0,0]
	v_pk_fma_f32 v[118:119], v[118:119], v[52:53], v[72:73]
	v_pk_fma_f32 v[120:121], v[120:121], v[54:55], v[74:75]
	v_pk_fma_f32 v[122:123], v[122:123], v[68:69], v[102:103]
	v_pk_fma_f32 v[124:125], v[124:125], v[70:71], v[104:105]
	v_pk_mul_f32 v[60:61], v[60:61], v[118:119]
	ds_read_b128 v[52:55], v8 offset:18432
	v_pk_fma_f32 v[68:69], v[120:121], v[62:63], v[60:61]
	ds_read_b128 v[60:63], v8 offset:18448
	v_pk_fma_f32 v[56:57], v[122:123], v[56:57], v[68:69]
	ds_read_b128 v[68:71], v8 offset:2048
	v_pk_fma_f32 v[72:73], v[124:125], v[58:59], v[56:57]
	ds_read_b128 v[56:59], v8 offset:2064
	ds_read_b32 v126, v9 offset:26624
	v_add_f32_e32 v72, v72, v73
	s_waitcnt lgkmcnt(11)
	v_pk_mul_f32 v[12:13], v[12:13], v[118:119]
	v_pk_mul_f32 v[130:131], v[20:21], v[128:129] op_sel_hi:[1,0]
	v_add_f32_dpp v20, v72, v72 quad_perm:[1,0,3,2] row_mask:0xf bank_mask:0xf bound_ctrl:1
	v_pk_fma_f32 v[12:13], v[120:121], v[14:15], v[12:13]
	v_pk_mul_f32 v[132:133], v[22:23], v[128:129] op_sel_hi:[1,0]
	v_add_f32_dpp v14, v20, v20 quad_perm:[2,3,0,1] row_mask:0xf bank_mask:0xf bound_ctrl:1
	v_pk_fma_f32 v[12:13], v[122:123], v[16:17], v[12:13]
	v_pk_mul_f32 v[160:161], v[24:25], v[128:129] op_sel_hi:[1,0]
	v_add_f32_dpp v14, v14, v14 row_half_mirror row_mask:0xf bank_mask:0xf bound_ctrl:1
	v_pk_fma_f32 v[12:13], v[124:125], v[18:19], v[12:13]
	v_pk_mul_f32 v[128:129], v[26:27], v[128:129] op_sel_hi:[1,0]
	v_cndmask_b32_e64 v11, v11, v14, s[60:61]
	v_add_f32_e32 v20, v12, v13
	ds_read_b128 v[12:15], v8 offset:35072
	ds_read_b128 v[16:19], v8 offset:35088
	v_add_f32_dpp v72, v20, v20 quad_perm:[1,0,3,2] row_mask:0xf bank_mask:0xf bound_ctrl:1
	ds_read_b128 v[20:23], v8 offset:10496
	ds_read_b128 v[24:27], v8 offset:10512
	v_add_f32_dpp v101, v72, v72 quad_perm:[2,3,0,1] row_mask:0xf bank_mask:0xf bound_ctrl:1
	ds_read_b128 v[72:75], v8 offset:43264
	ds_read_b128 v[102:105], v8 offset:43280
	v_add_f32_dpp v162, v101, v101 row_half_mirror row_mask:0xf bank_mask:0xf bound_ctrl:1
	v_pk_fma_f32 v[64:65], v[162:163], v[64:65], v[130:131] op_sel_hi:[0,1,1] neg_lo:[1,0,0] neg_hi:[1,0,0]
	v_pk_fma_f32 v[66:67], v[162:163], v[66:67], v[132:133] op_sel_hi:[0,1,1] neg_lo:[1,0,0] neg_hi:[1,0,0]
	v_pk_fma_f32 v[106:107], v[162:163], v[106:107], v[160:161] op_sel_hi:[0,1,1] neg_lo:[1,0,0] neg_hi:[1,0,0]
	v_pk_fma_f32 v[108:109], v[162:163], v[108:109], v[128:129] op_sel_hi:[0,1,1] neg_lo:[1,0,0] neg_hi:[1,0,0]
	v_pk_fma_f32 v[118:119], v[118:119], v[28:29], v[64:65]
	v_pk_fma_f32 v[120:121], v[120:121], v[30:31], v[66:67]
	v_pk_fma_f32 v[122:123], v[122:123], v[36:37], v[106:107]
	v_pk_fma_f32 v[124:125], v[124:125], v[38:39], v[108:109]
	v_pk_mul_f32 v[36:37], v[40:41], v[118:119]
	ds_read_b128 v[28:31], v8 offset:18688
	v_pk_fma_f32 v[40:41], v[120:121], v[42:43], v[36:37]
	ds_read_b128 v[36:39], v8 offset:18704
	v_pk_fma_f32 v[32:33], v[122:123], v[32:33], v[40:41]
	ds_read_b128 v[40:43], v8 offset:2304
	v_pk_fma_f32 v[64:65], v[124:125], v[34:35], v[32:33]
	ds_read_b128 v[32:35], v8 offset:2320
	ds_read_b32 v128, v9 offset:26880
	v_add_f32_e32 v64, v64, v65
	s_waitcnt lgkmcnt(11)
; #define LAS __attribute__((address_space(3)))
; __device__ __forceinline__ void scan_phase(const Args& a, int li, LAS unsigned char* lds) {
;     ...
;                 StepVec V0, V1, V2; SC_LOADV(V0, 0); SC_LOADV(V1, 1); float yk = 0.f, qprev = 0.f;
; #pragma unroll
;                 for (int t = 0; t < 32; ++t) {
;                     switch (t % 3) { case 0: SC_STEPF(V0, V2, (t + 2) & 31, (t + 7) & 7); break; case 1: SC_STEPF(V1, V0, (t + 2) & 31, (t + 7) & 7); break; default: SC_STEPF(V2, V1, (t + 2) & 31, (t + 7) & 7); break; }
;                     if ((t & 7) == 0 && t > 0) { *(LAS float*)(lds + SC_Y + (c & 1) * 4096 + ((t - 8) + cgp) * 128 + rl * 4) = yk; }
	v_pk_mul_f32 v[0:1], v[0:1], v[118:119]
	v_pk_mul_f32 v[130:131], v[52:53], v[126:127] op_sel_hi:[1,0]
	v_add_f32_dpp v52, v64, v64 quad_perm:[1,0,3,2] row_mask:0xf bank_mask:0xf bound_ctrl:1
	v_pk_fma_f32 v[0:1], v[120:121], v[2:3], v[0:1]
	v_pk_mul_f32 v[132:133], v[54:55], v[126:127] op_sel_hi:[1,0]
	v_add_f32_dpp v2, v52, v52 quad_perm:[2,3,0,1] row_mask:0xf bank_mask:0xf bound_ctrl:1
	v_pk_fma_f32 v[0:1], v[122:123], v[4:5], v[0:1]
	v_pk_mul_f32 v[160:161], v[60:61], v[126:127] op_sel_hi:[1,0]
	v_add_f32_dpp v2, v2, v2 row_half_mirror row_mask:0xf bank_mask:0xf bound_ctrl:1
	v_pk_fma_f32 v[0:1], v[124:125], v[6:7], v[0:1]
	v_pk_mul_f32 v[126:127], v[62:63], v[126:127] op_sel_hi:[1,0]
	v_cndmask_b32_e64 v11, v11, v2, s[38:39]
	v_add_f32_e32 v52, v0, v1
	ds_read_b128 v[0:3], v8 offset:35328
	ds_read_b128 v[4:7], v8 offset:35344
	v_add_f32_dpp v64, v52, v52 quad_perm:[1,0,3,2] row_mask:0xf bank_mask:0xf bound_ctrl:1
	ds_read_b128 v[52:55], v8 offset:10752
	ds_read_b128 v[60:63], v8 offset:10768
	v_add_f32_dpp v101, v64, v64 quad_perm:[2,3,0,1] row_mask:0xf bank_mask:0xf bound_ctrl:1
	ds_read_b128 v[64:67], v8 offset:43520
	ds_read_b128 v[106:109], v8 offset:43536
	v_add_f32_dpp v162, v101, v101 row_half_mirror row_mask:0xf bank_mask:0xf bound_ctrl:1
	v_pk_fma_f32 v[110:111], v[162:163], v[110:111], v[130:131] op_sel_hi:[0,1,1] neg_lo:[1,0,0] neg_hi:[1,0,0]
	v_pk_fma_f32 v[112:113], v[162:163], v[112:113], v[132:133] op_sel_hi:[0,1,1] neg_lo:[1,0,0] neg_hi:[1,0,0]
	v_pk_fma_f32 v[114:115], v[162:163], v[114:115], v[160:161] op_sel_hi:[0,1,1] neg_lo:[1,0,0] neg_hi:[1,0,0]
	v_pk_fma_f32 v[116:117], v[162:163], v[116:117], v[126:127] op_sel_hi:[0,1,1] neg_lo:[1,0,0] neg_hi:[1,0,0]
	v_pk_fma_f32 v[118:119], v[118:119], v[44:45], v[110:111]
	v_pk_fma_f32 v[120:121], v[120:121], v[46:47], v[112:113]
	v_pk_fma_f32 v[122:123], v[122:123], v[48:49], v[114:115]
	v_pk_fma_f32 v[124:125], v[124:125], v[50:51], v[116:117]
	v_pk_mul_f32 v[48:49], v[68:69], v[118:119]
	ds_read_b128 v[44:47], v8 offset:18944
	v_pk_fma_f32 v[68:69], v[120:121], v[70:71], v[48:49]
	ds_read_b128 v[48:51], v8 offset:18960
	v_pk_fma_f32 v[56:57], v[122:123], v[56:57], v[68:69]
	ds_read_b128 v[68:71], v8 offset:2560
	v_pk_fma_f32 v[110:111], v[124:125], v[58:59], v[56:57]
	ds_read_b128 v[56:59], v8 offset:2576
	ds_read_b32 v126, v9 offset:27136
	v_add_f32_e32 v101, v110, v111
	v_add_u32_e32 v110, v10, v143
	ds_write_b32 v110, v11
	s_waitcnt lgkmcnt(12)
	v_pk_mul_f32 v[12:13], v[12:13], v[118:119]
	v_pk_mul_f32 v[130:131], v[28:29], v[128:129] op_sel_hi:[1,0]
	v_add_f32_dpp v28, v101, v101 quad_perm:[1,0,3,2] row_mask:0xf bank_mask:0xf bound_ctrl:1
	v_pk_fma_f32 v[12:13], v[120:121], v[14:15], v[12:13]
	v_pk_mul_f32 v[132:133], v[30:31], v[128:129] op_sel_hi:[1,0]
	v_add_f32_dpp v14, v28, v28 quad_perm:[2,3,0,1] row_mask:0xf bank_mask:0xf bound_ctrl:1
	v_pk_fma_f32 v[12:13], v[122:123], v[16:17], v[12:13]
	v_pk_mul_f32 v[160:161], v[36:37], v[128:129] op_sel_hi:[1,0]
	v_add_f32_dpp v14, v14, v14 row_half_mirror row_mask:0xf bank_mask:0xf bound_ctrl:1
	v_pk_fma_f32 v[12:13], v[124:125], v[18:19], v[12:13]
	v_pk_mul_f32 v[128:129], v[38:39], v[128:129] op_sel_hi:[1,0]
	v_cndmask_b32_e64 v11, v11, v14, s[48:49]
	v_add_f32_e32 v28, v12, v13
	ds_read_b128 v[12:15], v8 offset:35584
	ds_read_b128 v[16:19], v8 offset:35600
	v_add_f32_dpp v101, v28, v28 quad_perm:[1,0,3,2] row_mask:0xf bank_mask:0xf bound_ctrl:1
	ds_read_b128 v[28:31], v8 offset:11008
	ds_read_b128 v[36:39], v8 offset:11024
	v_add_f32_dpp v101, v101, v101 quad_perm:[2,3,0,1] row_mask:0xf bank_mask:0xf bound_ctrl:1
	ds_read_b128 v[110:113], v8 offset:43776
	ds_read_b128 v[114:117], v8 offset:43792
	v_add_f32_dpp v162, v101, v101 row_half_mirror row_mask:0xf bank_mask:0xf bound_ctrl:1
	v_pk_fma_f32 v[72:73], v[162:163], v[72:73], v[130:131] op_sel_hi:[0,1,1] neg_lo:[1,0,0] neg_hi:[1,0,0]
	v_pk_fma_f32 v[74:75], v[162:163], v[74:75], v[132:133] op_sel_hi:[0,1,1] neg_lo:[1,0,0] neg_hi:[1,0,0]
	v_pk_fma_f32 v[102:103], v[162:163], v[102:103], v[160:161] op_sel_hi:[0,1,1] neg_lo:[1,0,0] neg_hi:[1,0,0]
	v_pk_fma_f32 v[104:105], v[162:163], v[104:105], v[128:129] op_sel_hi:[0,1,1] neg_lo:[1,0,0] neg_hi:[1,0,0]
	v_pk_fma_f32 v[118:119], v[118:119], v[20:21], v[72:73]
	v_pk_fma_f32 v[120:121], v[120:121], v[22:23], v[74:75]
	v_pk_fma_f32 v[122:123], v[122:123], v[24:25], v[102:103]
	v_pk_fma_f32 v[124:125], v[124:125], v[26:27], v[104:105]
	v_pk_mul_f32 v[24:25], v[40:41], v[118:119]
	ds_read_b128 v[20:23], v8 offset:19200
	v_pk_fma_f32 v[40:41], v[120:121], v[42:43], v[24:25]
	ds_read_b128 v[24:27], v8 offset:19216
	v_pk_fma_f32 v[32:33], v[122:123], v[32:33], v[40:41]
	ds_read_b128 v[40:43], v8 offset:2816
	v_pk_fma_f32 v[72:73], v[124:125], v[34:35], v[32:33]
	ds_read_b128 v[32:35], v8 offset:2832
	ds_read_b32 v128, v9 offset:27392
	v_add_f32_e32 v72, v72, v73
	s_waitcnt lgkmcnt(12)
; __device__ __forceinline__ void scan_phase(const Args& a, int li, LAS unsigned char* lds) {
;     ...
;                 StepVec V0, V1, V2; SC_LOADV(V0, 0); SC_LOADV(V1, 1); float yk = 0.f, qprev = 0.f;
; #pragma unroll
;                 for (int t = 0; t < 32; ++t) {
;                     switch (t % 3) { case 0: SC_STEPF(V0, V2, (t + 2) & 31, (t + 7) & 7); break; case 1: SC_STEPF(V1, V0, (t + 2) & 31, (t + 7) & 7); break; default: SC_STEPF(V2, V1, (t + 2) & 31, (t + 7) & 7); break; }
	v_pk_mul_f32 v[0:1], v[0:1], v[118:119]
	v_pk_mul_f32 v[130:131], v[44:45], v[126:127] op_sel_hi:[1,0]
	v_add_f32_dpp v44, v72, v72 quad_perm:[1,0,3,2] row_mask:0xf bank_mask:0xf bound_ctrl:1
	v_pk_fma_f32 v[0:1], v[120:121], v[2:3], v[0:1]
	v_pk_mul_f32 v[132:133], v[46:47], v[126:127] op_sel_hi:[1,0]
	v_add_f32_dpp v2, v44, v44 quad_perm:[2,3,0,1] row_mask:0xf bank_mask:0xf bound_ctrl:1
	v_pk_fma_f32 v[0:1], v[122:123], v[4:5], v[0:1]
	v_pk_mul_f32 v[160:161], v[48:49], v[126:127] op_sel_hi:[1,0]
	v_add_f32_dpp v2, v2, v2 row_half_mirror row_mask:0xf bank_mask:0xf bound_ctrl:1
	v_pk_fma_f32 v[0:1], v[124:125], v[6:7], v[0:1]
	v_pk_mul_f32 v[126:127], v[50:51], v[126:127] op_sel_hi:[1,0]
	v_cndmask_b32_e64 v11, v11, v2, s[50:51]
	v_add_f32_e32 v44, v0, v1
	ds_read_b128 v[0:3], v8 offset:35840
	ds_read_b128 v[4:7], v8 offset:35856
	v_add_f32_dpp v72, v44, v44 quad_perm:[1,0,3,2] row_mask:0xf bank_mask:0xf bound_ctrl:1
	ds_read_b128 v[44:47], v8 offset:11264
	ds_read_b128 v[48:51], v8 offset:11280
	v_add_f32_dpp v101, v72, v72 quad_perm:[2,3,0,1] row_mask:0xf bank_mask:0xf bound_ctrl:1
	ds_read_b128 v[72:75], v8 offset:44032
	ds_read_b128 v[102:105], v8 offset:44048
	v_add_f32_dpp v162, v101, v101 row_half_mirror row_mask:0xf bank_mask:0xf bound_ctrl:1
	v_pk_fma_f32 v[64:65], v[162:163], v[64:65], v[130:131] op_sel_hi:[0,1,1] neg_lo:[1,0,0] neg_hi:[1,0,0]
	v_pk_fma_f32 v[66:67], v[162:163], v[66:67], v[132:133] op_sel_hi:[0,1,1] neg_lo:[1,0,0] neg_hi:[1,0,0]
	v_pk_fma_f32 v[106:107], v[162:163], v[106:107], v[160:161] op_sel_hi:[0,1,1] neg_lo:[1,0,0] neg_hi:[1,0,0]
	v_pk_fma_f32 v[108:109], v[162:163], v[108:109], v[126:127] op_sel_hi:[0,1,1] neg_lo:[1,0,0] neg_hi:[1,0,0]
	v_pk_fma_f32 v[118:119], v[118:119], v[52:53], v[64:65]
	v_pk_fma_f32 v[120:121], v[120:121], v[54:55], v[66:67]
	v_pk_fma_f32 v[122:123], v[122:123], v[60:61], v[106:107]
	v_pk_fma_f32 v[124:125], v[124:125], v[62:63], v[108:109]
	v_pk_mul_f32 v[60:61], v[68:69], v[118:119]
	ds_read_b128 v[52:55], v8 offset:19456
	v_pk_fma_f32 v[64:65], v[120:121], v[70:71], v[60:61]
	ds_read_b128 v[60:63], v8 offset:19472
	v_pk_fma_f32 v[56:57], v[122:123], v[56:57], v[64:65]
	ds_read_b128 v[64:67], v8 offset:3072
	v_pk_fma_f32 v[68:69], v[124:125], v[58:59], v[56:57]
	ds_read_b128 v[56:59], v8 offset:3088
	ds_read_b32 v126, v9 offset:27648
	v_add_f32_e32 v68, v68, v69
	s_waitcnt lgkmcnt(11)
	v_pk_mul_f32 v[12:13], v[12:13], v[118:119]
	v_pk_mul_f32 v[130:131], v[20:21], v[128:129] op_sel_hi:[1,0]
	v_add_f32_dpp v20, v68, v68 quad_perm:[1,0,3,2] row_mask:0xf bank_mask:0xf bound_ctrl:1
	v_pk_fma_f32 v[12:13], v[120:121], v[14:15], v[12:13]
	v_pk_mul_f32 v[132:133], v[22:23], v[128:129] op_sel_hi:[1,0]
	v_add_f32_dpp v14, v20, v20 quad_perm:[2,3,0,1] row_mask:0xf bank_mask:0xf bound_ctrl:1
	v_pk_fma_f32 v[12:13], v[122:123], v[16:17], v[12:13]
	v_pk_mul_f32 v[160:161], v[24:25], v[128:129] op_sel_hi:[1,0]
	v_add_f32_dpp v14, v14, v14 row_half_mirror row_mask:0xf bank_mask:0xf bound_ctrl:1
	v_pk_fma_f32 v[12:13], v[124:125], v[18:19], v[12:13]
	v_pk_mul_f32 v[128:129], v[26:27], v[128:129] op_sel_hi:[1,0]
	v_cndmask_b32_e64 v11, v11, v14, s[52:53]
	v_add_f32_e32 v20, v12, v13
	ds_read_b128 v[12:15], v8 offset:36096
	ds_read_b128 v[16:19], v8 offset:36112
	v_add_f32_dpp v68, v20, v20 quad_perm:[1,0,3,2] row_mask:0xf bank_mask:0xf bound_ctrl:1
	ds_read_b128 v[20:23], v8 offset:11520
	ds_read_b128 v[24:27], v8 offset:11536
	v_add_f32_dpp v101, v68, v68 quad_perm:[2,3,0,1] row_mask:0xf bank_mask:0xf bound_ctrl:1
	ds_read_b128 v[68:71], v8 offset:44288
	ds_read_b128 v[106:109], v8 offset:44304
	v_add_f32_dpp v162, v101, v101 row_half_mirror row_mask:0xf bank_mask:0xf bound_ctrl:1
	v_pk_fma_f32 v[110:111], v[162:163], v[110:111], v[130:131] op_sel_hi:[0,1,1] neg_lo:[1,0,0] neg_hi:[1,0,0]
	v_pk_fma_f32 v[112:113], v[162:163], v[112:113], v[132:133] op_sel_hi:[0,1,1] neg_lo:[1,0,0] neg_hi:[1,0,0]
	v_pk_fma_f32 v[114:115], v[162:163], v[114:115], v[160:161] op_sel_hi:[0,1,1] neg_lo:[1,0,0] neg_hi:[1,0,0]
	v_pk_fma_f32 v[116:117], v[162:163], v[116:117], v[128:129] op_sel_hi:[0,1,1] neg_lo:[1,0,0] neg_hi:[1,0,0]
	v_pk_fma_f32 v[118:119], v[118:119], v[28:29], v[110:111]
	v_pk_fma_f32 v[120:121], v[120:121], v[30:31], v[112:113]
	v_pk_fma_f32 v[122:123], v[122:123], v[36:37], v[114:115]
	v_pk_fma_f32 v[124:125], v[124:125], v[38:39], v[116:117]
	v_pk_mul_f32 v[36:37], v[40:41], v[118:119]
	ds_read_b128 v[28:31], v8 offset:19712
	v_pk_fma_f32 v[40:41], v[120:121], v[42:43], v[36:37]
	ds_read_b128 v[36:39], v8 offset:19728
	v_pk_fma_f32 v[32:33], v[122:123], v[32:33], v[40:41]
	ds_read_b128 v[40:43], v8 offset:3328
	v_pk_fma_f32 v[110:111], v[124:125], v[34:35], v[32:33]
	ds_read_b128 v[32:35], v8 offset:3344
	ds_read_b32 v128, v9 offset:27904
	v_add_f32_e32 v101, v110, v111
	s_waitcnt lgkmcnt(11)
; __device__ __forceinline__ void scan_phase(const Args& a, int li, LAS unsigned char* lds) {
;     ...
;                 StepVec V0, V1, V2; SC_LOADV(V0, 0); SC_LOADV(V1, 1); float yk = 0.f, qprev = 0.f;
; #pragma unroll
;                 for (int t = 0; t < 32; ++t) {
;                     switch (t % 3) { case 0: SC_STEPF(V0, V2, (t + 2) & 31, (t + 7) & 7); break; case 1: SC_STEPF(V1, V0, (t + 2) & 31, (t + 7) & 7); break; default: SC_STEPF(V2, V1, (t + 2) & 31, (t + 7) & 7); break; }
	v_pk_mul_f32 v[0:1], v[0:1], v[118:119]
	v_pk_mul_f32 v[130:131], v[52:53], v[126:127] op_sel_hi:[1,0]
	v_add_f32_dpp v52, v101, v101 quad_perm:[1,0,3,2] row_mask:0xf bank_mask:0xf bound_ctrl:1
	v_pk_fma_f32 v[0:1], v[120:121], v[2:3], v[0:1]
	v_pk_mul_f32 v[132:133], v[54:55], v[126:127] op_sel_hi:[1,0]
	v_add_f32_dpp v2, v52, v52 quad_perm:[2,3,0,1] row_mask:0xf bank_mask:0xf bound_ctrl:1
	v_pk_fma_f32 v[0:1], v[122:123], v[4:5], v[0:1]
	v_pk_mul_f32 v[160:161], v[60:61], v[126:127] op_sel_hi:[1,0]
	v_add_f32_dpp v2, v2, v2 row_half_mirror row_mask:0xf bank_mask:0xf bound_ctrl:1
	v_pk_fma_f32 v[0:1], v[124:125], v[6:7], v[0:1]
	v_pk_mul_f32 v[126:127], v[62:63], v[126:127] op_sel_hi:[1,0]
	v_cndmask_b32_e64 v11, v11, v2, s[54:55]
	v_add_f32_e32 v52, v0, v1
	ds_read_b128 v[0:3], v8 offset:36352
	ds_read_b128 v[4:7], v8 offset:36368
	v_add_f32_dpp v101, v52, v52 quad_perm:[1,0,3,2] row_mask:0xf bank_mask:0xf bound_ctrl:1
	ds_read_b128 v[52:55], v8 offset:11776
	ds_read_b128 v[60:63], v8 offset:11792
	v_add_f32_dpp v101, v101, v101 quad_perm:[2,3,0,1] row_mask:0xf bank_mask:0xf bound_ctrl:1
	ds_read_b128 v[110:113], v8 offset:44544
	ds_read_b128 v[114:117], v8 offset:44560
	v_add_f32_dpp v162, v101, v101 row_half_mirror row_mask:0xf bank_mask:0xf bound_ctrl:1
	v_pk_fma_f32 v[72:73], v[162:163], v[72:73], v[130:131] op_sel_hi:[0,1,1] neg_lo:[1,0,0] neg_hi:[1,0,0]
	v_pk_fma_f32 v[74:75], v[162:163], v[74:75], v[132:133] op_sel_hi:[0,1,1] neg_lo:[1,0,0] neg_hi:[1,0,0]
	v_pk_fma_f32 v[102:103], v[162:163], v[102:103], v[160:161] op_sel_hi:[0,1,1] neg_lo:[1,0,0] neg_hi:[1,0,0]
	v_pk_fma_f32 v[104:105], v[162:163], v[104:105], v[126:127] op_sel_hi:[0,1,1] neg_lo:[1,0,0] neg_hi:[1,0,0]
	v_pk_fma_f32 v[118:119], v[118:119], v[44:45], v[72:73]
	v_pk_fma_f32 v[120:121], v[120:121], v[46:47], v[74:75]
	v_pk_fma_f32 v[122:123], v[122:123], v[48:49], v[102:103]
	v_pk_fma_f32 v[124:125], v[124:125], v[50:51], v[104:105]
	v_pk_mul_f32 v[48:49], v[64:65], v[118:119]
	ds_read_b128 v[44:47], v8 offset:19968
	v_pk_fma_f32 v[64:65], v[120:121], v[66:67], v[48:49]
	ds_read_b128 v[48:51], v8 offset:19984
	v_pk_fma_f32 v[56:57], v[122:123], v[56:57], v[64:65]
	ds_read_b128 v[64:67], v8 offset:3584
	v_pk_fma_f32 v[72:73], v[124:125], v[58:59], v[56:57]
	ds_read_b128 v[56:59], v8 offset:3600
	ds_read_b32 v126, v9 offset:28160
	v_add_f32_e32 v72, v72, v73
	s_waitcnt lgkmcnt(11)
	v_pk_mul_f32 v[12:13], v[12:13], v[118:119]
	v_pk_mul_f32 v[130:131], v[28:29], v[128:129] op_sel_hi:[1,0]
	v_add_f32_dpp v28, v72, v72 quad_perm:[1,0,3,2] row_mask:0xf bank_mask:0xf bound_ctrl:1
	v_pk_fma_f32 v[12:13], v[120:121], v[14:15], v[12:13]
	v_pk_mul_f32 v[132:133], v[30:31], v[128:129] op_sel_hi:[1,0]
	v_add_f32_dpp v14, v28, v28 quad_perm:[2,3,0,1] row_mask:0xf bank_mask:0xf bound_ctrl:1
	v_pk_fma_f32 v[12:13], v[122:123], v[16:17], v[12:13]
	v_pk_mul_f32 v[160:161], v[36:37], v[128:129] op_sel_hi:[1,0]
	v_add_f32_dpp v14, v14, v14 row_half_mirror row_mask:0xf bank_mask:0xf bound_ctrl:1
	v_pk_fma_f32 v[12:13], v[124:125], v[18:19], v[12:13]
	v_pk_mul_f32 v[128:129], v[38:39], v[128:129] op_sel_hi:[1,0]
	v_cndmask_b32_e64 v11, v11, v14, s[56:57]
	v_add_f32_e32 v28, v12, v13
	ds_read_b128 v[12:15], v8 offset:36608
	ds_read_b128 v[16:19], v8 offset:36624
	v_add_f32_dpp v72, v28, v28 quad_perm:[1,0,3,2] row_mask:0xf bank_mask:0xf bound_ctrl:1
	ds_read_b128 v[28:31], v8 offset:12032
	ds_read_b128 v[36:39], v8 offset:12048
	v_add_f32_dpp v101, v72, v72 quad_perm:[2,3,0,1] row_mask:0xf bank_mask:0xf bound_ctrl:1
	ds_read_b128 v[72:75], v8 offset:44800
	ds_read_b128 v[102:105], v8 offset:44816
	v_add_f32_dpp v162, v101, v101 row_half_mirror row_mask:0xf bank_mask:0xf bound_ctrl:1
	v_pk_fma_f32 v[68:69], v[162:163], v[68:69], v[130:131] op_sel_hi:[0,1,1] neg_lo:[1,0,0] neg_hi:[1,0,0]
	v_pk_fma_f32 v[70:71], v[162:163], v[70:71], v[132:133] op_sel_hi:[0,1,1] neg_lo:[1,0,0] neg_hi:[1,0,0]
	v_pk_fma_f32 v[106:107], v[162:163], v[106:107], v[160:161] op_sel_hi:[0,1,1] neg_lo:[1,0,0] neg_hi:[1,0,0]
	v_pk_fma_f32 v[108:109], v[162:163], v[108:109], v[128:129] op_sel_hi:[0,1,1] neg_lo:[1,0,0] neg_hi:[1,0,0]
	v_pk_fma_f32 v[118:119], v[118:119], v[20:21], v[68:69]
	v_pk_fma_f32 v[120:121], v[120:121], v[22:23], v[70:71]
	v_pk_fma_f32 v[122:123], v[122:123], v[24:25], v[106:107]
	v_pk_fma_f32 v[124:125], v[124:125], v[26:27], v[108:109]
	v_pk_mul_f32 v[24:25], v[40:41], v[118:119]
	ds_read_b128 v[20:23], v8 offset:20224
	v_pk_fma_f32 v[40:41], v[120:121], v[42:43], v[24:25]
	ds_read_b128 v[24:27], v8 offset:20240
	v_pk_fma_f32 v[32:33], v[122:123], v[32:33], v[40:41]
	ds_read_b128 v[40:43], v8 offset:3840
	v_pk_fma_f32 v[68:69], v[124:125], v[34:35], v[32:33]
	ds_read_b128 v[32:35], v8 offset:3856
	ds_read_b32 v128, v9 offset:28416
	v_add_f32_e32 v68, v68, v69
	s_waitcnt lgkmcnt(11)
; #define LAS __attribute__((address_space(3)))
; #define SB_ __builtin_amdgcn_sched_barrier(0)
; __device__ __forceinline__ void scan_phase(const Args& a, int li, LAS unsigned char* lds) {
;     ...
;                 StepVec V0, V1, V2; SC_LOADV(V0, 0); SC_LOADV(V1, 1); float yk = 0.f, qprev = 0.f;
; #pragma unroll
;                 for (int t = 0; t < 32; ++t) {
;                     switch (t % 3) { case 0: SC_STEPF(V0, V2, (t + 2) & 31, (t + 7) & 7); break; case 1: SC_STEPF(V1, V0, (t + 2) & 31, (t + 7) & 7); break; default: SC_STEPF(V2, V1, (t + 2) & 31, (t + 7) & 7); break; }
;                     if ((t & 7) == 0 && t > 0) { *(LAS float*)(lds + SC_Y + (c & 1) * 4096 + ((t - 8) + cgp) * 128 + rl * 4) = yk; }
;                     SB_; }
	v_pk_mul_f32 v[0:1], v[0:1], v[118:119]
	v_pk_mul_f32 v[130:131], v[44:45], v[126:127] op_sel_hi:[1,0]
	v_add_f32_dpp v44, v68, v68 quad_perm:[1,0,3,2] row_mask:0xf bank_mask:0xf bound_ctrl:1
	v_pk_fma_f32 v[0:1], v[120:121], v[2:3], v[0:1]
	v_pk_mul_f32 v[132:133], v[46:47], v[126:127] op_sel_hi:[1,0]
	v_add_f32_dpp v2, v44, v44 quad_perm:[2,3,0,1] row_mask:0xf bank_mask:0xf bound_ctrl:1
	v_pk_fma_f32 v[0:1], v[122:123], v[4:5], v[0:1]
	v_pk_mul_f32 v[160:161], v[48:49], v[126:127] op_sel_hi:[1,0]
	v_add_f32_dpp v2, v2, v2 row_half_mirror row_mask:0xf bank_mask:0xf bound_ctrl:1
	v_pk_fma_f32 v[0:1], v[124:125], v[6:7], v[0:1]
	v_pk_mul_f32 v[126:127], v[50:51], v[126:127] op_sel_hi:[1,0]
	v_cndmask_b32_e64 v11, v11, v2, s[58:59]
	v_add_f32_e32 v44, v0, v1
	ds_read_b128 v[0:3], v8 offset:36864
	ds_read_b128 v[4:7], v8 offset:36880
	v_add_f32_dpp v68, v44, v44 quad_perm:[1,0,3,2] row_mask:0xf bank_mask:0xf bound_ctrl:1
	ds_read_b128 v[44:47], v8 offset:12288
	ds_read_b128 v[48:51], v8 offset:12304
	v_add_f32_dpp v101, v68, v68 quad_perm:[2,3,0,1] row_mask:0xf bank_mask:0xf bound_ctrl:1
	ds_read_b128 v[68:71], v8 offset:45056
	ds_read_b128 v[106:109], v8 offset:45072
	v_add_f32_dpp v162, v101, v101 row_half_mirror row_mask:0xf bank_mask:0xf bound_ctrl:1
	v_pk_fma_f32 v[110:111], v[162:163], v[110:111], v[130:131] op_sel_hi:[0,1,1] neg_lo:[1,0,0] neg_hi:[1,0,0]
	v_pk_fma_f32 v[112:113], v[162:163], v[112:113], v[132:133] op_sel_hi:[0,1,1] neg_lo:[1,0,0] neg_hi:[1,0,0]
	v_pk_fma_f32 v[114:115], v[162:163], v[114:115], v[160:161] op_sel_hi:[0,1,1] neg_lo:[1,0,0] neg_hi:[1,0,0]
	v_pk_fma_f32 v[116:117], v[162:163], v[116:117], v[126:127] op_sel_hi:[0,1,1] neg_lo:[1,0,0] neg_hi:[1,0,0]
	v_pk_fma_f32 v[118:119], v[118:119], v[52:53], v[110:111]
	v_pk_fma_f32 v[120:121], v[120:121], v[54:55], v[112:113]
	v_pk_fma_f32 v[122:123], v[122:123], v[60:61], v[114:115]
	v_pk_fma_f32 v[124:125], v[124:125], v[62:63], v[116:117]
	v_pk_mul_f32 v[60:61], v[64:65], v[118:119]
	ds_read_b128 v[52:55], v8 offset:20480
	v_pk_fma_f32 v[64:65], v[120:121], v[66:67], v[60:61]
	ds_read_b128 v[60:63], v8 offset:20496
	v_pk_fma_f32 v[56:57], v[122:123], v[56:57], v[64:65]
	ds_read_b128 v[64:67], v8 offset:4096
	v_pk_fma_f32 v[110:111], v[124:125], v[58:59], v[56:57]
	ds_read_b128 v[56:59], v8 offset:4112
	ds_read_b32 v126, v9 offset:28672
	v_add_f32_e32 v101, v110, v111
	s_waitcnt lgkmcnt(11)
	v_pk_mul_f32 v[12:13], v[12:13], v[118:119]
	v_pk_mul_f32 v[130:131], v[20:21], v[128:129] op_sel_hi:[1,0]
	v_add_f32_dpp v20, v101, v101 quad_perm:[1,0,3,2] row_mask:0xf bank_mask:0xf bound_ctrl:1
	v_pk_fma_f32 v[12:13], v[120:121], v[14:15], v[12:13]
	v_pk_mul_f32 v[132:133], v[22:23], v[128:129] op_sel_hi:[1,0]
	v_add_f32_dpp v14, v20, v20 quad_perm:[2,3,0,1] row_mask:0xf bank_mask:0xf bound_ctrl:1
	v_pk_fma_f32 v[12:13], v[122:123], v[16:17], v[12:13]
	v_pk_mul_f32 v[160:161], v[24:25], v[128:129] op_sel_hi:[1,0]
	v_add_f32_dpp v14, v14, v14 row_half_mirror row_mask:0xf bank_mask:0xf bound_ctrl:1
	v_pk_fma_f32 v[12:13], v[124:125], v[18:19], v[12:13]
	v_pk_mul_f32 v[128:129], v[26:27], v[128:129] op_sel_hi:[1,0]
	v_cndmask_b32_e64 v11, v11, v14, s[60:61]
	v_add_f32_e32 v20, v12, v13
	ds_read_b128 v[12:15], v8 offset:37120
	ds_read_b128 v[16:19], v8 offset:37136
	v_add_f32_dpp v101, v20, v20 quad_perm:[1,0,3,2] row_mask:0xf bank_mask:0xf bound_ctrl:1
	ds_read_b128 v[20:23], v8 offset:12544
	ds_read_b128 v[24:27], v8 offset:12560
	v_add_f32_dpp v101, v101, v101 quad_perm:[2,3,0,1] row_mask:0xf bank_mask:0xf bound_ctrl:1
	ds_read_b128 v[110:113], v8 offset:45312
	ds_read_b128 v[114:117], v8 offset:45328
	v_add_f32_dpp v162, v101, v101 row_half_mirror row_mask:0xf bank_mask:0xf bound_ctrl:1
	v_pk_fma_f32 v[72:73], v[162:163], v[72:73], v[130:131] op_sel_hi:[0,1,1] neg_lo:[1,0,0] neg_hi:[1,0,0]
	v_pk_fma_f32 v[74:75], v[162:163], v[74:75], v[132:133] op_sel_hi:[0,1,1] neg_lo:[1,0,0] neg_hi:[1,0,0]
	v_pk_fma_f32 v[102:103], v[162:163], v[102:103], v[160:161] op_sel_hi:[0,1,1] neg_lo:[1,0,0] neg_hi:[1,0,0]
	v_pk_fma_f32 v[104:105], v[162:163], v[104:105], v[128:129] op_sel_hi:[0,1,1] neg_lo:[1,0,0] neg_hi:[1,0,0]
	v_pk_fma_f32 v[128:129], v[118:119], v[28:29], v[72:73]
	v_pk_fma_f32 v[130:131], v[120:121], v[30:31], v[74:75]
	v_pk_fma_f32 v[122:123], v[122:123], v[36:37], v[102:103]
	v_pk_fma_f32 v[124:125], v[124:125], v[38:39], v[104:105]
	v_pk_mul_f32 v[36:37], v[40:41], v[128:129]
	ds_read_b128 v[28:31], v8 offset:20736
	v_pk_fma_f32 v[40:41], v[130:131], v[42:43], v[36:37]
	ds_read_b128 v[36:39], v8 offset:20752
	v_pk_fma_f32 v[32:33], v[122:123], v[32:33], v[40:41]
	ds_read_b128 v[40:43], v8 offset:4352
	v_pk_fma_f32 v[72:73], v[124:125], v[34:35], v[32:33]
	ds_read_b128 v[32:35], v8 offset:4368
	ds_read_b32 v132, v9 offset:28928
	v_add_f32_e32 v72, v72, v73
	s_waitcnt lgkmcnt(11)
; #define LAS __attribute__((address_space(3)))
; #define SB_ __builtin_amdgcn_sched_barrier(0)
; __device__ __forceinline__ void scan_phase(const Args& a, int li, LAS unsigned char* lds) {
;     ...
;                 StepVec V0, V1, V2; SC_LOADV(V0, 0); SC_LOADV(V1, 1); float yk = 0.f, qprev = 0.f;
; #pragma unroll
;                 for (int t = 0; t < 32; ++t) {
;                     switch (t % 3) { case 0: SC_STEPF(V0, V2, (t + 2) & 31, (t + 7) & 7); break; case 1: SC_STEPF(V1, V0, (t + 2) & 31, (t + 7) & 7); break; default: SC_STEPF(V2, V1, (t + 2) & 31, (t + 7) & 7); break; }
;                     if ((t & 7) == 0 && t > 0) { *(LAS float*)(lds + SC_Y + (c & 1) * 4096 + ((t - 8) + cgp) * 128 + rl * 4) = yk; }
;                     SB_; }
	v_pk_mul_f32 v[0:1], v[0:1], v[128:129]
	v_pk_mul_f32 v[160:161], v[52:53], v[126:127] op_sel_hi:[1,0]
	v_add_f32_dpp v52, v72, v72 quad_perm:[1,0,3,2] row_mask:0xf bank_mask:0xf bound_ctrl:1
	v_pk_fma_f32 v[0:1], v[130:131], v[2:3], v[0:1]
	v_pk_mul_f32 v[162:163], v[54:55], v[126:127] op_sel_hi:[1,0]
	v_add_f32_dpp v2, v52, v52 quad_perm:[2,3,0,1] row_mask:0xf bank_mask:0xf bound_ctrl:1
	v_pk_fma_f32 v[0:1], v[122:123], v[4:5], v[0:1]
	v_pk_mul_f32 v[164:165], v[60:61], v[126:127] op_sel_hi:[1,0]
	v_add_f32_dpp v2, v2, v2 row_half_mirror row_mask:0xf bank_mask:0xf bound_ctrl:1
	v_pk_fma_f32 v[0:1], v[124:125], v[6:7], v[0:1]
	v_pk_mul_f32 v[6:7], v[62:63], v[126:127] op_sel_hi:[1,0]
	v_cndmask_b32_e64 v101, v11, v2, s[38:39]
	v_add_f32_e32 v0, v0, v1
	ds_read_b128 v[2:5], v8 offset:37376
	ds_read_b128 v[52:55], v8 offset:37392
	v_add_f32_dpp v0, v0, v0 quad_perm:[1,0,3,2] row_mask:0xf bank_mask:0xf bound_ctrl:1
	ds_read_b128 v[60:63], v8 offset:12800
	ds_read_b128 v[72:75], v8 offset:12816
	v_add_f32_dpp v0, v0, v0 quad_perm:[2,3,0,1] row_mask:0xf bank_mask:0xf bound_ctrl:1
	ds_read_b128 v[102:105], v8 offset:45568
	ds_read_b128 v[118:121], v8 offset:45584
	v_add_f32_dpp v0, v0, v0 row_half_mirror row_mask:0xf bank_mask:0xf bound_ctrl:1
	v_pk_fma_f32 v[68:69], v[0:1], v[68:69], v[160:161] op_sel_hi:[0,1,1] neg_lo:[1,0,0] neg_hi:[1,0,0]
	v_pk_fma_f32 v[70:71], v[0:1], v[70:71], v[162:163] op_sel_hi:[0,1,1] neg_lo:[1,0,0] neg_hi:[1,0,0]
	v_pk_fma_f32 v[106:107], v[0:1], v[106:107], v[164:165] op_sel_hi:[0,1,1] neg_lo:[1,0,0] neg_hi:[1,0,0]
	v_pk_fma_f32 v[0:1], v[0:1], v[108:109], v[6:7] op_sel_hi:[0,1,1] neg_lo:[1,0,0] neg_hi:[1,0,0]
	v_pk_fma_f32 v[6:7], v[128:129], v[44:45], v[68:69]
	v_pk_fma_f32 v[126:127], v[130:131], v[46:47], v[70:71]
	v_pk_fma_f32 v[122:123], v[122:123], v[48:49], v[106:107]
	v_pk_fma_f32 v[124:125], v[124:125], v[50:51], v[0:1]
	v_pk_mul_f32 v[0:1], v[64:65], v[6:7]
	ds_read_b128 v[44:47], v8 offset:20992
	v_pk_fma_f32 v[0:1], v[126:127], v[66:67], v[0:1]
	ds_read_b128 v[48:51], v8 offset:21008
	v_pk_fma_f32 v[0:1], v[122:123], v[56:57], v[0:1]
	ds_read_b128 v[64:67], v8 offset:4608
	v_pk_fma_f32 v[0:1], v[124:125], v[58:59], v[0:1]
	ds_read_b128 v[56:59], v8 offset:4624
	ds_read_b32 v128, v9 offset:29184
	v_add_f32_e32 v1, v0, v1
	v_add_u32_e32 v0, v10, v144
	ds_write_b32 v0, v101 offset:2048
	s_waitcnt lgkmcnt(12)
	v_pk_mul_f32 v[10:11], v[12:13], v[6:7]
	v_pk_mul_f32 v[130:131], v[28:29], v[132:133] op_sel_hi:[1,0]
	v_add_f32_dpp v1, v1, v1 quad_perm:[1,0,3,2] row_mask:0xf bank_mask:0xf bound_ctrl:1
	v_pk_fma_f32 v[10:11], v[126:127], v[14:15], v[10:11]
	v_pk_mul_f32 v[160:161], v[30:31], v[132:133] op_sel_hi:[1,0]
	v_add_f32_dpp v1, v1, v1 quad_perm:[2,3,0,1] row_mask:0xf bank_mask:0xf bound_ctrl:1
	v_pk_fma_f32 v[10:11], v[122:123], v[16:17], v[10:11]
	v_pk_mul_f32 v[162:163], v[36:37], v[132:133] op_sel_hi:[1,0]
	v_add_f32_dpp v1, v1, v1 row_half_mirror row_mask:0xf bank_mask:0xf bound_ctrl:1
	v_pk_fma_f32 v[10:11], v[124:125], v[18:19], v[10:11]
	v_pk_mul_f32 v[18:19], v[38:39], v[132:133] op_sel_hi:[1,0]
	v_cndmask_b32_e64 v1, v101, v1, s[48:49]
	v_add_f32_e32 v28, v10, v11
	ds_read_b128 v[10:13], v8 offset:37632
	ds_read_b128 v[14:17], v8 offset:37648
	v_add_f32_dpp v68, v28, v28 quad_perm:[1,0,3,2] row_mask:0xf bank_mask:0xf bound_ctrl:1
	ds_read_b128 v[28:31], v8 offset:13056
	ds_read_b128 v[36:39], v8 offset:13072
	v_add_f32_dpp v101, v68, v68 quad_perm:[2,3,0,1] row_mask:0xf bank_mask:0xf bound_ctrl:1
	ds_read_b128 v[68:71], v8 offset:45824
	ds_read_b128 v[106:109], v8 offset:45840
	v_add_f32_dpp v132, v101, v101 row_half_mirror row_mask:0xf bank_mask:0xf bound_ctrl:1
	v_pk_fma_f32 v[110:111], v[132:133], v[110:111], v[130:131] op_sel_hi:[0,1,1] neg_lo:[1,0,0] neg_hi:[1,0,0]
	v_pk_fma_f32 v[112:113], v[132:133], v[112:113], v[160:161] op_sel_hi:[0,1,1] neg_lo:[1,0,0] neg_hi:[1,0,0]
	v_pk_fma_f32 v[114:115], v[132:133], v[114:115], v[162:163] op_sel_hi:[0,1,1] neg_lo:[1,0,0] neg_hi:[1,0,0]
	v_pk_fma_f32 v[18:19], v[132:133], v[116:117], v[18:19] op_sel_hi:[0,1,1] neg_lo:[1,0,0] neg_hi:[1,0,0]
	v_pk_fma_f32 v[6:7], v[6:7], v[20:21], v[110:111]
	v_pk_fma_f32 v[126:127], v[126:127], v[22:23], v[112:113]
	v_pk_fma_f32 v[122:123], v[122:123], v[24:25], v[114:115]
	v_pk_fma_f32 v[26:27], v[124:125], v[26:27], v[18:19]
	v_pk_mul_f32 v[22:23], v[40:41], v[6:7]
	ds_read_b128 v[18:21], v8 offset:21248
	v_pk_fma_f32 v[40:41], v[126:127], v[42:43], v[22:23]
	ds_read_b128 v[22:25], v8 offset:21264
	v_pk_fma_f32 v[32:33], v[122:123], v[32:33], v[40:41]
	ds_read_b128 v[40:43], v8 offset:4864
	v_pk_fma_f32 v[110:111], v[26:27], v[34:35], v[32:33]
	ds_read_b128 v[32:35], v8 offset:4880
	ds_read_b32 v124, v9 offset:29440
	v_add_f32_e32 v101, v110, v111
	s_waitcnt lgkmcnt(12)
; #define LAS __attribute__((address_space(3)))
; #define SB_ __builtin_amdgcn_sched_barrier(0)
; __device__ __forceinline__ void scan_phase(const Args& a, int li, LAS unsigned char* lds) {
;     ...
;                 StepVec V0, V1, V2; SC_LOADV(V0, 0); SC_LOADV(V1, 1); float yk = 0.f, qprev = 0.f;
; #pragma unroll
;                 for (int t = 0; t < 32; ++t) {
;                     switch (t % 3) { case 0: SC_STEPF(V0, V2, (t + 2) & 31, (t + 7) & 7); break; case 1: SC_STEPF(V1, V0, (t + 2) & 31, (t + 7) & 7); break; default: SC_STEPF(V2, V1, (t + 2) & 31, (t + 7) & 7); break; }
;                     if ((t & 7) == 0 && t > 0) { *(LAS float*)(lds + SC_Y + (c & 1) * 4096 + ((t - 8) + cgp) * 128 + rl * 4) = yk; }
;                     SB_; }
	v_pk_mul_f32 v[2:3], v[2:3], v[6:7]
	v_pk_mul_f32 v[130:131], v[44:45], v[128:129] op_sel_hi:[1,0]
	v_add_f32_dpp v44, v101, v101 quad_perm:[1,0,3,2] row_mask:0xf bank_mask:0xf bound_ctrl:1
	v_pk_fma_f32 v[2:3], v[126:127], v[4:5], v[2:3]
	v_pk_mul_f32 v[132:133], v[46:47], v[128:129] op_sel_hi:[1,0]
	v_add_f32_dpp v4, v44, v44 quad_perm:[2,3,0,1] row_mask:0xf bank_mask:0xf bound_ctrl:1
	v_pk_fma_f32 v[2:3], v[122:123], v[52:53], v[2:3]
	v_pk_mul_f32 v[160:161], v[48:49], v[128:129] op_sel_hi:[1,0]
	v_add_f32_dpp v4, v4, v4 row_half_mirror row_mask:0xf bank_mask:0xf bound_ctrl:1
	v_pk_fma_f32 v[2:3], v[26:27], v[54:55], v[2:3]
	v_pk_mul_f32 v[128:129], v[50:51], v[128:129] op_sel_hi:[1,0]
	v_cndmask_b32_e64 v1, v1, v4, s[50:51]
	v_add_f32_e32 v48, v2, v3
	ds_read_b128 v[2:5], v8 offset:37888
	ds_read_b128 v[44:47], v8 offset:37904
	v_add_f32_dpp v101, v48, v48 quad_perm:[1,0,3,2] row_mask:0xf bank_mask:0xf bound_ctrl:1
	ds_read_b128 v[48:51], v8 offset:13312
	ds_read_b128 v[52:55], v8 offset:13328
	v_add_f32_dpp v101, v101, v101 quad_perm:[2,3,0,1] row_mask:0xf bank_mask:0xf bound_ctrl:1
	ds_read_b128 v[110:113], v8 offset:46080
	ds_read_b128 v[114:117], v8 offset:46096
	v_add_f32_dpp v162, v101, v101 row_half_mirror row_mask:0xf bank_mask:0xf bound_ctrl:1
	v_pk_fma_f32 v[102:103], v[162:163], v[102:103], v[130:131] op_sel_hi:[0,1,1] neg_lo:[1,0,0] neg_hi:[1,0,0]
	v_pk_fma_f32 v[104:105], v[162:163], v[104:105], v[132:133] op_sel_hi:[0,1,1] neg_lo:[1,0,0] neg_hi:[1,0,0]
	v_pk_fma_f32 v[118:119], v[162:163], v[118:119], v[160:161] op_sel_hi:[0,1,1] neg_lo:[1,0,0] neg_hi:[1,0,0]
	v_pk_fma_f32 v[120:121], v[162:163], v[120:121], v[128:129] op_sel_hi:[0,1,1] neg_lo:[1,0,0] neg_hi:[1,0,0]
	v_pk_fma_f32 v[6:7], v[6:7], v[60:61], v[102:103]
	v_pk_fma_f32 v[126:127], v[126:127], v[62:63], v[104:105]
	v_pk_fma_f32 v[122:123], v[122:123], v[72:73], v[118:119]
	v_pk_fma_f32 v[26:27], v[26:27], v[74:75], v[120:121]
	v_pk_mul_f32 v[64:65], v[64:65], v[6:7]
	ds_read_b128 v[60:63], v8 offset:21504
	v_pk_fma_f32 v[72:73], v[126:127], v[66:67], v[64:65]
	ds_read_b128 v[64:67], v8 offset:21520
	v_pk_fma_f32 v[56:57], v[122:123], v[56:57], v[72:73]
	ds_read_b128 v[72:75], v8 offset:5120
	v_pk_fma_f32 v[102:103], v[26:27], v[58:59], v[56:57]
	ds_read_b128 v[56:59], v8 offset:5136
	ds_read_b32 v128, v9 offset:29696
	v_add_f32_e32 v101, v102, v103
	s_waitcnt lgkmcnt(11)
	v_pk_mul_f32 v[10:11], v[10:11], v[6:7]
	v_pk_mul_f32 v[130:131], v[18:19], v[124:125] op_sel_hi:[1,0]
	v_add_f32_dpp v18, v101, v101 quad_perm:[1,0,3,2] row_mask:0xf bank_mask:0xf bound_ctrl:1
	v_pk_fma_f32 v[10:11], v[126:127], v[12:13], v[10:11]
	v_pk_mul_f32 v[132:133], v[20:21], v[124:125] op_sel_hi:[1,0]
	v_add_f32_dpp v12, v18, v18 quad_perm:[2,3,0,1] row_mask:0xf bank_mask:0xf bound_ctrl:1
	v_pk_fma_f32 v[10:11], v[122:123], v[14:15], v[10:11]
	v_pk_mul_f32 v[160:161], v[22:23], v[124:125] op_sel_hi:[1,0]
	v_add_f32_dpp v12, v12, v12 row_half_mirror row_mask:0xf bank_mask:0xf bound_ctrl:1
	v_pk_fma_f32 v[10:11], v[26:27], v[16:17], v[10:11]
	v_pk_mul_f32 v[124:125], v[24:25], v[124:125] op_sel_hi:[1,0]
	v_cndmask_b32_e64 v1, v1, v12, s[52:53]
	v_add_f32_e32 v18, v10, v11
	ds_read_b128 v[10:13], v8 offset:38144
	ds_read_b128 v[14:17], v8 offset:38160
	v_add_f32_dpp v101, v18, v18 quad_perm:[1,0,3,2] row_mask:0xf bank_mask:0xf bound_ctrl:1
	ds_read_b128 v[18:21], v8 offset:13568
	ds_read_b128 v[22:25], v8 offset:13584
	v_add_f32_dpp v101, v101, v101 quad_perm:[2,3,0,1] row_mask:0xf bank_mask:0xf bound_ctrl:1
	ds_read_b128 v[102:105], v8 offset:46336
	ds_read_b128 v[118:121], v8 offset:46352
	v_add_f32_dpp v162, v101, v101 row_half_mirror row_mask:0xf bank_mask:0xf bound_ctrl:1
	v_pk_fma_f32 v[68:69], v[162:163], v[68:69], v[130:131] op_sel_hi:[0,1,1] neg_lo:[1,0,0] neg_hi:[1,0,0]
	v_pk_fma_f32 v[70:71], v[162:163], v[70:71], v[132:133] op_sel_hi:[0,1,1] neg_lo:[1,0,0] neg_hi:[1,0,0]
	v_pk_fma_f32 v[106:107], v[162:163], v[106:107], v[160:161] op_sel_hi:[0,1,1] neg_lo:[1,0,0] neg_hi:[1,0,0]
	v_pk_fma_f32 v[108:109], v[162:163], v[108:109], v[124:125] op_sel_hi:[0,1,1] neg_lo:[1,0,0] neg_hi:[1,0,0]
	v_pk_fma_f32 v[6:7], v[6:7], v[28:29], v[68:69]
	v_pk_fma_f32 v[124:125], v[126:127], v[30:31], v[70:71]
	v_pk_fma_f32 v[122:123], v[122:123], v[36:37], v[106:107]
	v_pk_fma_f32 v[126:127], v[26:27], v[38:39], v[108:109]
	v_pk_mul_f32 v[30:31], v[40:41], v[6:7]
	ds_read_b128 v[26:29], v8 offset:21760
	v_pk_fma_f32 v[30:31], v[124:125], v[42:43], v[30:31]
	ds_read_b128 v[36:39], v8 offset:21776
	v_pk_fma_f32 v[40:41], v[122:123], v[32:33], v[30:31]
	ds_read_b128 v[30:33], v8 offset:5376
	v_pk_fma_f32 v[34:35], v[126:127], v[34:35], v[40:41]
	ds_read_b128 v[40:43], v8 offset:5392
	ds_read_b32 v130, v9 offset:29952
	v_add_f32_e32 v68, v34, v35
	s_waitcnt lgkmcnt(11)
; #define LAS __attribute__((address_space(3)))
; #define SB_ __builtin_amdgcn_sched_barrier(0)
; __device__ __forceinline__ void scan_phase(const Args& a, int li, LAS unsigned char* lds) {
;     ...
;                 StepVec V0, V1, V2; SC_LOADV(V0, 0); SC_LOADV(V1, 1); float yk = 0.f, qprev = 0.f;
; #pragma unroll
;                 for (int t = 0; t < 32; ++t) {
;                     switch (t % 3) { case 0: SC_STEPF(V0, V2, (t + 2) & 31, (t + 7) & 7); break; case 1: SC_STEPF(V1, V0, (t + 2) & 31, (t + 7) & 7); break; default: SC_STEPF(V2, V1, (t + 2) & 31, (t + 7) & 7); break; }
;                     if ((t & 7) == 0 && t > 0) { *(LAS float*)(lds + SC_Y + (c & 1) * 4096 + ((t - 8) + cgp) * 128 + rl * 4) = yk; }
;                     SB_; }
	v_pk_mul_f32 v[2:3], v[2:3], v[6:7]
	v_pk_mul_f32 v[34:35], v[60:61], v[128:129] op_sel_hi:[1,0]
	v_add_f32_dpp v60, v68, v68 quad_perm:[1,0,3,2] row_mask:0xf bank_mask:0xf bound_ctrl:1
	v_pk_fma_f32 v[2:3], v[124:125], v[4:5], v[2:3]
	v_pk_mul_f32 v[132:133], v[62:63], v[128:129] op_sel_hi:[1,0]
	v_add_f32_dpp v4, v60, v60 quad_perm:[2,3,0,1] row_mask:0xf bank_mask:0xf bound_ctrl:1
	v_pk_fma_f32 v[2:3], v[122:123], v[44:45], v[2:3]
	v_pk_mul_f32 v[160:161], v[64:65], v[128:129] op_sel_hi:[1,0]
	v_add_f32_dpp v4, v4, v4 row_half_mirror row_mask:0xf bank_mask:0xf bound_ctrl:1
	v_pk_fma_f32 v[2:3], v[126:127], v[46:47], v[2:3]
	v_pk_mul_f32 v[128:129], v[66:67], v[128:129] op_sel_hi:[1,0]
	v_cndmask_b32_e64 v1, v1, v4, s[54:55]
	v_add_f32_e32 v60, v2, v3
	ds_read_b128 v[2:5], v8 offset:38400
	ds_read_b128 v[44:47], v8 offset:38416
	v_add_f32_dpp v68, v60, v60 quad_perm:[1,0,3,2] row_mask:0xf bank_mask:0xf bound_ctrl:1
	ds_read_b128 v[60:63], v8 offset:13824
	ds_read_b128 v[64:67], v8 offset:13840
	v_add_f32_dpp v101, v68, v68 quad_perm:[2,3,0,1] row_mask:0xf bank_mask:0xf bound_ctrl:1
	ds_read_b128 v[68:71], v8 offset:46592
	ds_read_b128 v[106:109], v8 offset:46608
	v_add_f32_dpp v162, v101, v101 row_half_mirror row_mask:0xf bank_mask:0xf bound_ctrl:1
	v_pk_fma_f32 v[34:35], v[162:163], v[110:111], v[34:35] op_sel_hi:[0,1,1] neg_lo:[1,0,0] neg_hi:[1,0,0]
	v_pk_fma_f32 v[110:111], v[162:163], v[112:113], v[132:133] op_sel_hi:[0,1,1] neg_lo:[1,0,0] neg_hi:[1,0,0]
	v_pk_fma_f32 v[112:113], v[162:163], v[114:115], v[160:161] op_sel_hi:[0,1,1] neg_lo:[1,0,0] neg_hi:[1,0,0]
	v_pk_fma_f32 v[114:115], v[162:163], v[116:117], v[128:129] op_sel_hi:[0,1,1] neg_lo:[1,0,0] neg_hi:[1,0,0]
	v_pk_fma_f32 v[6:7], v[6:7], v[48:49], v[34:35]
	v_pk_fma_f32 v[124:125], v[124:125], v[50:51], v[110:111]
	v_pk_fma_f32 v[122:123], v[122:123], v[52:53], v[112:113]
	v_pk_fma_f32 v[126:127], v[126:127], v[54:55], v[114:115]
	v_pk_mul_f32 v[34:35], v[72:73], v[6:7]
	ds_read_b128 v[48:51], v8 offset:22016
	v_pk_fma_f32 v[34:35], v[124:125], v[74:75], v[34:35]
	ds_read_b128 v[52:55], v8 offset:22032
	v_pk_fma_f32 v[34:35], v[122:123], v[56:57], v[34:35]
	ds_read_b128 v[72:75], v8 offset:5632
	v_pk_fma_f32 v[34:35], v[126:127], v[58:59], v[34:35]
	ds_read_b128 v[56:59], v8 offset:5648
	ds_read_b32 v128, v9 offset:30208
	v_add_f32_e32 v34, v34, v35
	s_waitcnt lgkmcnt(11)
	v_pk_mul_f32 v[10:11], v[10:11], v[6:7]
	v_pk_mul_f32 v[132:133], v[26:27], v[130:131] op_sel_hi:[1,0]
	v_add_f32_dpp v26, v34, v34 quad_perm:[1,0,3,2] row_mask:0xf bank_mask:0xf bound_ctrl:1
	v_pk_fma_f32 v[10:11], v[124:125], v[12:13], v[10:11]
	v_pk_mul_f32 v[160:161], v[28:29], v[130:131] op_sel_hi:[1,0]
	v_add_f32_dpp v12, v26, v26 quad_perm:[2,3,0,1] row_mask:0xf bank_mask:0xf bound_ctrl:1
	v_pk_fma_f32 v[10:11], v[122:123], v[14:15], v[10:11]
	v_pk_mul_f32 v[162:163], v[36:37], v[130:131] op_sel_hi:[1,0]
	v_add_f32_dpp v12, v12, v12 row_half_mirror row_mask:0xf bank_mask:0xf bound_ctrl:1
	v_pk_fma_f32 v[10:11], v[126:127], v[16:17], v[10:11]
	v_pk_mul_f32 v[38:39], v[38:39], v[130:131] op_sel_hi:[1,0]
	v_cndmask_b32_e64 v1, v1, v12, s[56:57]
	v_add_f32_e32 v26, v10, v11
	ds_read_b128 v[10:13], v8 offset:38656
	ds_read_b128 v[14:17], v8 offset:38672
	v_add_f32_dpp v101, v26, v26 quad_perm:[1,0,3,2] row_mask:0xf bank_mask:0xf bound_ctrl:1
	ds_read_b128 v[26:29], v8 offset:14080
	ds_read_b128 v[34:37], v8 offset:14096
	v_add_f32_dpp v101, v101, v101 quad_perm:[2,3,0,1] row_mask:0xf bank_mask:0xf bound_ctrl:1
	ds_read_b128 v[110:113], v8 offset:46848
	ds_read_b128 v[114:117], v8 offset:46864
	v_add_f32_dpp v130, v101, v101 row_half_mirror row_mask:0xf bank_mask:0xf bound_ctrl:1
	v_pk_fma_f32 v[102:103], v[130:131], v[102:103], v[132:133] op_sel_hi:[0,1,1] neg_lo:[1,0,0] neg_hi:[1,0,0]
	v_pk_fma_f32 v[104:105], v[130:131], v[104:105], v[160:161] op_sel_hi:[0,1,1] neg_lo:[1,0,0] neg_hi:[1,0,0]
	v_pk_fma_f32 v[118:119], v[130:131], v[118:119], v[162:163] op_sel_hi:[0,1,1] neg_lo:[1,0,0] neg_hi:[1,0,0]
	v_pk_fma_f32 v[38:39], v[130:131], v[120:121], v[38:39] op_sel_hi:[0,1,1] neg_lo:[1,0,0] neg_hi:[1,0,0]
	v_pk_fma_f32 v[6:7], v[6:7], v[18:19], v[102:103]
	v_pk_fma_f32 v[124:125], v[124:125], v[20:21], v[104:105]
	v_pk_fma_f32 v[122:123], v[122:123], v[22:23], v[118:119]
	v_pk_fma_f32 v[126:127], v[126:127], v[24:25], v[38:39]
	v_pk_mul_f32 v[22:23], v[30:31], v[6:7]
	ds_read_b128 v[18:21], v8 offset:22272
	v_pk_fma_f32 v[30:31], v[124:125], v[32:33], v[22:23]
	ds_read_b128 v[22:25], v8 offset:22288
	v_pk_fma_f32 v[38:39], v[122:123], v[40:41], v[30:31]
	ds_read_b128 v[30:33], v8 offset:5888
	v_pk_fma_f32 v[42:43], v[126:127], v[42:43], v[38:39]
	ds_read_b128 v[38:41], v8 offset:5904
	ds_read_b32 v130, v9 offset:30464
	v_add_f32_e32 v42, v42, v43
	s_waitcnt lgkmcnt(11)
; #define LAS __attribute__((address_space(3)))
; #define SB_ __builtin_amdgcn_sched_barrier(0)
; __device__ __forceinline__ void scan_phase(const Args& a, int li, LAS unsigned char* lds) {
;     ...
;                 StepVec V0, V1, V2; SC_LOADV(V0, 0); SC_LOADV(V1, 1); float yk = 0.f, qprev = 0.f;
; #pragma unroll
;                 for (int t = 0; t < 32; ++t) {
;                     switch (t % 3) { case 0: SC_STEPF(V0, V2, (t + 2) & 31, (t + 7) & 7); break; case 1: SC_STEPF(V1, V0, (t + 2) & 31, (t + 7) & 7); break; default: SC_STEPF(V2, V1, (t + 2) & 31, (t + 7) & 7); break; }
;                     if ((t & 7) == 0 && t > 0) { *(LAS float*)(lds + SC_Y + (c & 1) * 4096 + ((t - 8) + cgp) * 128 + rl * 4) = yk; }
;                     SB_; }
	v_pk_mul_f32 v[2:3], v[2:3], v[6:7]
	v_pk_mul_f32 v[132:133], v[48:49], v[128:129] op_sel_hi:[1,0]
	v_add_f32_dpp v42, v42, v42 quad_perm:[1,0,3,2] row_mask:0xf bank_mask:0xf bound_ctrl:1
	v_pk_fma_f32 v[2:3], v[124:125], v[4:5], v[2:3]
	v_pk_mul_f32 v[160:161], v[50:51], v[128:129] op_sel_hi:[1,0]
	v_add_f32_dpp v4, v42, v42 quad_perm:[2,3,0,1] row_mask:0xf bank_mask:0xf bound_ctrl:1
	v_pk_fma_f32 v[2:3], v[122:123], v[44:45], v[2:3]
	v_pk_mul_f32 v[162:163], v[52:53], v[128:129] op_sel_hi:[1,0]
	v_add_f32_dpp v4, v4, v4 row_half_mirror row_mask:0xf bank_mask:0xf bound_ctrl:1
	v_pk_fma_f32 v[2:3], v[126:127], v[46:47], v[2:3]
	v_pk_mul_f32 v[54:55], v[54:55], v[128:129] op_sel_hi:[1,0]
	v_cndmask_b32_e64 v1, v1, v4, s[58:59]
	v_add_f32_e32 v46, v2, v3
	ds_read_b128 v[2:5], v8 offset:38912
	ds_read_b128 v[42:45], v8 offset:38928
	v_add_f32_dpp v101, v46, v46 quad_perm:[1,0,3,2] row_mask:0xf bank_mask:0xf bound_ctrl:1
	ds_read_b128 v[46:49], v8 offset:14336
	ds_read_b128 v[50:53], v8 offset:14352
	v_add_f32_dpp v101, v101, v101 quad_perm:[2,3,0,1] row_mask:0xf bank_mask:0xf bound_ctrl:1
	ds_read_b128 v[102:105], v8 offset:47104
	ds_read_b128 v[118:121], v8 offset:47120
	v_add_f32_dpp v128, v101, v101 row_half_mirror row_mask:0xf bank_mask:0xf bound_ctrl:1
	v_pk_fma_f32 v[68:69], v[128:129], v[68:69], v[132:133] op_sel_hi:[0,1,1] neg_lo:[1,0,0] neg_hi:[1,0,0]
	v_pk_fma_f32 v[70:71], v[128:129], v[70:71], v[160:161] op_sel_hi:[0,1,1] neg_lo:[1,0,0] neg_hi:[1,0,0]
	v_pk_fma_f32 v[106:107], v[128:129], v[106:107], v[162:163] op_sel_hi:[0,1,1] neg_lo:[1,0,0] neg_hi:[1,0,0]
	v_pk_fma_f32 v[54:55], v[128:129], v[108:109], v[54:55] op_sel_hi:[0,1,1] neg_lo:[1,0,0] neg_hi:[1,0,0]
	v_pk_fma_f32 v[6:7], v[6:7], v[60:61], v[68:69]
	v_pk_fma_f32 v[124:125], v[124:125], v[62:63], v[70:71]
	v_pk_fma_f32 v[122:123], v[122:123], v[64:65], v[106:107]
	v_pk_fma_f32 v[126:127], v[126:127], v[66:67], v[54:55]
	v_pk_mul_f32 v[54:55], v[72:73], v[6:7]
	ds_read_b128 v[60:63], v8 offset:22528
	v_pk_fma_f32 v[54:55], v[124:125], v[74:75], v[54:55]
	ds_read_b128 v[64:67], v8 offset:22544
	v_pk_fma_f32 v[68:69], v[122:123], v[56:57], v[54:55]
	ds_read_b128 v[54:57], v8 offset:6144
	v_pk_fma_f32 v[58:59], v[126:127], v[58:59], v[68:69]
	ds_read_b128 v[68:71], v8 offset:6160
	ds_read_b32 v128, v9 offset:30720
	v_add_f32_e32 v72, v58, v59
	s_waitcnt lgkmcnt(11)
	v_pk_mul_f32 v[10:11], v[10:11], v[6:7]
	v_pk_mul_f32 v[58:59], v[18:19], v[130:131] op_sel_hi:[1,0]
	v_add_f32_dpp v18, v72, v72 quad_perm:[1,0,3,2] row_mask:0xf bank_mask:0xf bound_ctrl:1
	v_pk_fma_f32 v[10:11], v[124:125], v[12:13], v[10:11]
	v_pk_mul_f32 v[132:133], v[20:21], v[130:131] op_sel_hi:[1,0]
	v_add_f32_dpp v12, v18, v18 quad_perm:[2,3,0,1] row_mask:0xf bank_mask:0xf bound_ctrl:1
	v_pk_fma_f32 v[10:11], v[122:123], v[14:15], v[10:11]
	v_pk_mul_f32 v[160:161], v[22:23], v[130:131] op_sel_hi:[1,0]
	v_add_f32_dpp v12, v12, v12 row_half_mirror row_mask:0xf bank_mask:0xf bound_ctrl:1
	v_pk_fma_f32 v[10:11], v[126:127], v[16:17], v[10:11]
	v_pk_mul_f32 v[130:131], v[24:25], v[130:131] op_sel_hi:[1,0]
	v_cndmask_b32_e64 v1, v1, v12, s[60:61]
	v_add_f32_e32 v18, v10, v11
	ds_read_b128 v[10:13], v8 offset:39168
	ds_read_b128 v[14:17], v8 offset:39184
	v_add_f32_dpp v72, v18, v18 quad_perm:[1,0,3,2] row_mask:0xf bank_mask:0xf bound_ctrl:1
	ds_read_b128 v[18:21], v8 offset:14592
	ds_read_b128 v[22:25], v8 offset:14608
	v_add_f32_dpp v101, v72, v72 quad_perm:[2,3,0,1] row_mask:0xf bank_mask:0xf bound_ctrl:1
	ds_read_b128 v[72:75], v8 offset:47360
	ds_read_b128 v[106:109], v8 offset:47376
	v_add_f32_dpp v162, v101, v101 row_half_mirror row_mask:0xf bank_mask:0xf bound_ctrl:1
	v_pk_fma_f32 v[58:59], v[162:163], v[110:111], v[58:59] op_sel_hi:[0,1,1] neg_lo:[1,0,0] neg_hi:[1,0,0]
	v_pk_fma_f32 v[110:111], v[162:163], v[112:113], v[132:133] op_sel_hi:[0,1,1] neg_lo:[1,0,0] neg_hi:[1,0,0]
	v_pk_fma_f32 v[112:113], v[162:163], v[114:115], v[160:161] op_sel_hi:[0,1,1] neg_lo:[1,0,0] neg_hi:[1,0,0]
	v_pk_fma_f32 v[114:115], v[162:163], v[116:117], v[130:131] op_sel_hi:[0,1,1] neg_lo:[1,0,0] neg_hi:[1,0,0]
	v_pk_fma_f32 v[6:7], v[6:7], v[26:27], v[58:59]
	v_pk_fma_f32 v[124:125], v[124:125], v[28:29], v[110:111]
	v_pk_fma_f32 v[122:123], v[122:123], v[34:35], v[112:113]
	v_pk_fma_f32 v[126:127], v[126:127], v[36:37], v[114:115]
	v_pk_mul_f32 v[30:31], v[30:31], v[6:7]
	ds_read_b128 v[26:29], v8 offset:22784
	v_pk_fma_f32 v[34:35], v[124:125], v[32:33], v[30:31]
	ds_read_b128 v[30:33], v8 offset:22800
	v_pk_fma_f32 v[38:39], v[122:123], v[38:39], v[34:35]
	ds_read_b128 v[34:37], v8 offset:6400
	v_pk_fma_f32 v[58:59], v[126:127], v[40:41], v[38:39]
	ds_read_b128 v[38:41], v8 offset:6416
	ds_read_b32 v130, v9 offset:30976
	v_add_f32_e32 v58, v58, v59
	s_waitcnt lgkmcnt(11)
; #define LAS __attribute__((address_space(3)))
; #define SB_ __builtin_amdgcn_sched_barrier(0)
; __device__ __forceinline__ void scan_phase(const Args& a, int li, LAS unsigned char* lds) {
;     ...
;                 StepVec V0, V1, V2; SC_LOADV(V0, 0); SC_LOADV(V1, 1); float yk = 0.f, qprev = 0.f;
; #pragma unroll
;                 for (int t = 0; t < 32; ++t) {
;                     switch (t % 3) { case 0: SC_STEPF(V0, V2, (t + 2) & 31, (t + 7) & 7); break; case 1: SC_STEPF(V1, V0, (t + 2) & 31, (t + 7) & 7); break; default: SC_STEPF(V2, V1, (t + 2) & 31, (t + 7) & 7); break; }
;                     if ((t & 7) == 0 && t > 0) { *(LAS float*)(lds + SC_Y + (c & 1) * 4096 + ((t - 8) + cgp) * 128 + rl * 4) = yk; }
;                     SB_; }
	v_pk_mul_f32 v[2:3], v[2:3], v[6:7]
	v_pk_mul_f32 v[132:133], v[60:61], v[128:129] op_sel_hi:[1,0]
	v_add_f32_dpp v58, v58, v58 quad_perm:[1,0,3,2] row_mask:0xf bank_mask:0xf bound_ctrl:1
	v_pk_fma_f32 v[2:3], v[124:125], v[4:5], v[2:3]
	v_pk_mul_f32 v[160:161], v[62:63], v[128:129] op_sel_hi:[1,0]
	v_add_f32_dpp v4, v58, v58 quad_perm:[2,3,0,1] row_mask:0xf bank_mask:0xf bound_ctrl:1
	v_pk_fma_f32 v[2:3], v[122:123], v[42:43], v[2:3]
	v_pk_mul_f32 v[162:163], v[64:65], v[128:129] op_sel_hi:[1,0]
	v_add_f32_dpp v4, v4, v4 row_half_mirror row_mask:0xf bank_mask:0xf bound_ctrl:1
	v_pk_fma_f32 v[2:3], v[126:127], v[44:45], v[2:3]
	v_pk_mul_f32 v[66:67], v[66:67], v[128:129] op_sel_hi:[1,0]
	v_cndmask_b32_e64 v101, v1, v4, s[38:39]
	v_add_f32_e32 v1, v2, v3
	ds_read_b128 v[2:5], v8 offset:39424
	ds_read_b128 v[42:45], v8 offset:39440
	v_add_f32_dpp v1, v1, v1 quad_perm:[1,0,3,2] row_mask:0xf bank_mask:0xf bound_ctrl:1
	ds_read_b128 v[58:61], v8 offset:14848
	ds_read_b128 v[62:65], v8 offset:14864
	v_add_f32_dpp v1, v1, v1 quad_perm:[2,3,0,1] row_mask:0xf bank_mask:0xf bound_ctrl:1
	ds_read_b128 v[110:113], v8 offset:47616
	ds_read_b128 v[114:117], v8 offset:47632
	v_add_f32_dpp v128, v1, v1 row_half_mirror row_mask:0xf bank_mask:0xf bound_ctrl:1
	v_pk_fma_f32 v[102:103], v[128:129], v[102:103], v[132:133] op_sel_hi:[0,1,1] neg_lo:[1,0,0] neg_hi:[1,0,0]
	v_pk_fma_f32 v[104:105], v[128:129], v[104:105], v[160:161] op_sel_hi:[0,1,1] neg_lo:[1,0,0] neg_hi:[1,0,0]
	v_pk_fma_f32 v[118:119], v[128:129], v[118:119], v[162:163] op_sel_hi:[0,1,1] neg_lo:[1,0,0] neg_hi:[1,0,0]
	v_pk_fma_f32 v[66:67], v[128:129], v[120:121], v[66:67] op_sel_hi:[0,1,1] neg_lo:[1,0,0] neg_hi:[1,0,0]
	v_pk_fma_f32 v[6:7], v[6:7], v[46:47], v[102:103]
	v_pk_fma_f32 v[124:125], v[124:125], v[48:49], v[104:105]
	v_pk_fma_f32 v[122:123], v[122:123], v[50:51], v[118:119]
	v_pk_fma_f32 v[126:127], v[126:127], v[52:53], v[66:67]
	v_pk_mul_f32 v[50:51], v[54:55], v[6:7]
	ds_read_b128 v[46:49], v8 offset:23040
	v_pk_fma_f32 v[54:55], v[124:125], v[56:57], v[50:51]
	ds_read_b128 v[50:53], v8 offset:23056
	v_pk_fma_f32 v[66:67], v[122:123], v[68:69], v[54:55]
	ds_read_b128 v[54:57], v8 offset:6656
	v_pk_fma_f32 v[70:71], v[126:127], v[70:71], v[66:67]
	ds_read_b128 v[66:69], v8 offset:6672
	ds_read_b32 v128, v9 offset:31232
	v_add_f32_e32 v102, v70, v71
	ds_write_b32 v0, v101 offset:3072
	s_waitcnt lgkmcnt(12)
	v_pk_mul_f32 v[0:1], v[10:11], v[6:7]
	v_pk_mul_f32 v[70:71], v[26:27], v[130:131] op_sel_hi:[1,0]
	v_add_f32_dpp v10, v102, v102 quad_perm:[1,0,3,2] row_mask:0xf bank_mask:0xf bound_ctrl:1
	v_pk_fma_f32 v[0:1], v[124:125], v[12:13], v[0:1]
	v_pk_mul_f32 v[132:133], v[28:29], v[130:131] op_sel_hi:[1,0]
	v_add_f32_dpp v10, v10, v10 quad_perm:[2,3,0,1] row_mask:0xf bank_mask:0xf bound_ctrl:1
	v_pk_fma_f32 v[0:1], v[122:123], v[14:15], v[0:1]
	v_pk_mul_f32 v[160:161], v[30:31], v[130:131] op_sel_hi:[1,0]
	v_add_f32_dpp v10, v10, v10 row_half_mirror row_mask:0xf bank_mask:0xf bound_ctrl:1
	v_pk_fma_f32 v[0:1], v[126:127], v[16:17], v[0:1]
	v_pk_mul_f32 v[130:131], v[32:33], v[130:131] op_sel_hi:[1,0]
	v_cndmask_b32_e64 v101, v101, v10, s[48:49]
	v_add_f32_e32 v0, v0, v1
	ds_read_b128 v[10:13], v8 offset:39680
	ds_read_b128 v[14:17], v8 offset:39696
	v_add_f32_dpp v0, v0, v0 quad_perm:[1,0,3,2] row_mask:0xf bank_mask:0xf bound_ctrl:1
	ds_read_b128 v[26:29], v8 offset:15104
	ds_read_b128 v[30:33], v8 offset:15120
	v_add_f32_dpp v0, v0, v0 quad_perm:[2,3,0,1] row_mask:0xf bank_mask:0xf bound_ctrl:1
	ds_read_b128 v[102:105], v8 offset:47872
	ds_read_b128 v[118:121], v8 offset:47888
	v_add_f32_dpp v0, v0, v0 row_half_mirror row_mask:0xf bank_mask:0xf bound_ctrl:1
	v_pk_fma_f32 v[70:71], v[0:1], v[72:73], v[70:71] op_sel_hi:[0,1,1] neg_lo:[1,0,0] neg_hi:[1,0,0]
	v_pk_fma_f32 v[72:73], v[0:1], v[74:75], v[132:133] op_sel_hi:[0,1,1] neg_lo:[1,0,0] neg_hi:[1,0,0]
	v_pk_fma_f32 v[74:75], v[0:1], v[106:107], v[160:161] op_sel_hi:[0,1,1] neg_lo:[1,0,0] neg_hi:[1,0,0]
	v_pk_fma_f32 v[0:1], v[0:1], v[108:109], v[130:131] op_sel_hi:[0,1,1] neg_lo:[1,0,0] neg_hi:[1,0,0]
	v_pk_fma_f32 v[106:107], v[6:7], v[18:19], v[70:71]
	v_pk_fma_f32 v[108:109], v[124:125], v[20:21], v[72:73]
	v_pk_fma_f32 v[74:75], v[122:123], v[22:23], v[74:75]
	v_pk_fma_f32 v[122:123], v[126:127], v[24:25], v[0:1]
	v_pk_mul_f32 v[0:1], v[34:35], v[106:107]
	ds_read_b128 v[18:21], v8 offset:23296
	v_pk_fma_f32 v[0:1], v[108:109], v[36:37], v[0:1]
	ds_read_b128 v[22:25], v8 offset:23312
	v_pk_fma_f32 v[0:1], v[74:75], v[38:39], v[0:1]
	ds_read_b128 v[34:37], v8 offset:6912
	v_pk_fma_f32 v[0:1], v[122:123], v[40:41], v[0:1]
	ds_read_b128 v[38:41], v8 offset:6928
	ds_read_b32 v124, v9 offset:31488
	v_add_f32_e32 v6, v0, v1
	s_waitcnt lgkmcnt(12)
; #define LAS __attribute__((address_space(3)))
; #define SB_ __builtin_amdgcn_sched_barrier(0)
; __device__ __forceinline__ void scan_phase(const Args& a, int li, LAS unsigned char* lds) {
;     ...
;                 StepVec V0, V1, V2; SC_LOADV(V0, 0); SC_LOADV(V1, 1); float yk = 0.f, qprev = 0.f;
; #pragma unroll
;                 for (int t = 0; t < 32; ++t) {
;                     switch (t % 3) { case 0: SC_STEPF(V0, V2, (t + 2) & 31, (t + 7) & 7); break; case 1: SC_STEPF(V1, V0, (t + 2) & 31, (t + 7) & 7); break; default: SC_STEPF(V2, V1, (t + 2) & 31, (t + 7) & 7); break; }
;                     if ((t & 7) == 0 && t > 0) { *(LAS float*)(lds + SC_Y + (c & 1) * 4096 + ((t - 8) + cgp) * 128 + rl * 4) = yk; }
;                     SB_; }
	v_pk_mul_f32 v[0:1], v[2:3], v[106:107]
	v_pk_mul_f32 v[126:127], v[46:47], v[128:129] op_sel_hi:[1,0]
	v_add_f32_dpp v2, v6, v6 quad_perm:[1,0,3,2] row_mask:0xf bank_mask:0xf bound_ctrl:1
	v_pk_fma_f32 v[0:1], v[108:109], v[4:5], v[0:1]
	v_pk_mul_f32 v[130:131], v[48:49], v[128:129] op_sel_hi:[1,0]
	v_add_f32_dpp v2, v2, v2 quad_perm:[2,3,0,1] row_mask:0xf bank_mask:0xf bound_ctrl:1
	v_pk_fma_f32 v[0:1], v[74:75], v[42:43], v[0:1]
	v_pk_mul_f32 v[132:133], v[50:51], v[128:129] op_sel_hi:[1,0]
	v_add_f32_dpp v2, v2, v2 row_half_mirror row_mask:0xf bank_mask:0xf bound_ctrl:1
	v_pk_fma_f32 v[0:1], v[122:123], v[44:45], v[0:1]
	v_pk_mul_f32 v[128:129], v[52:53], v[128:129] op_sel_hi:[1,0]
	v_cndmask_b32_e64 v101, v101, v2, s[50:51]
	v_add_f32_e32 v42, v0, v1
	ds_read_b128 v[0:3], v8 offset:39936
	ds_read_b128 v[4:7], v8 offset:39952
	v_add_f32_dpp v50, v42, v42 quad_perm:[1,0,3,2] row_mask:0xf bank_mask:0xf bound_ctrl:1
	ds_read_b128 v[42:45], v8 offset:15360
	ds_read_b128 v[46:49], v8 offset:15376
	v_add_f32_dpp v125, v50, v50 quad_perm:[2,3,0,1] row_mask:0xf bank_mask:0xf bound_ctrl:1
	ds_read_b128 v[50:53], v8 offset:48128
	ds_read_b128 v[70:73], v8 offset:48144
	v_add_f32_dpp v160, v125, v125 row_half_mirror row_mask:0xf bank_mask:0xf bound_ctrl:1
	v_pk_fma_f32 v[110:111], v[160:161], v[110:111], v[126:127] op_sel_hi:[0,1,1] neg_lo:[1,0,0] neg_hi:[1,0,0]
	v_pk_fma_f32 v[112:113], v[160:161], v[112:113], v[130:131] op_sel_hi:[0,1,1] neg_lo:[1,0,0] neg_hi:[1,0,0]
	v_pk_fma_f32 v[114:115], v[160:161], v[114:115], v[132:133] op_sel_hi:[0,1,1] neg_lo:[1,0,0] neg_hi:[1,0,0]
	v_pk_fma_f32 v[116:117], v[160:161], v[116:117], v[128:129] op_sel_hi:[0,1,1] neg_lo:[1,0,0] neg_hi:[1,0,0]
	v_pk_fma_f32 v[126:127], v[106:107], v[58:59], v[110:111]
	v_pk_fma_f32 v[128:129], v[108:109], v[60:61], v[112:113]
	v_pk_fma_f32 v[74:75], v[74:75], v[62:63], v[114:115]
	v_pk_fma_f32 v[114:115], v[122:123], v[64:65], v[116:117]
	v_pk_mul_f32 v[54:55], v[54:55], v[126:127]
	ds_read_b128 v[58:61], v8 offset:23552
	v_pk_fma_f32 v[62:63], v[128:129], v[56:57], v[54:55]
	ds_read_b128 v[54:57], v8 offset:23568
	v_pk_fma_f32 v[66:67], v[74:75], v[66:67], v[62:63]
	ds_read_b128 v[62:65], v8 offset:7168
	v_pk_fma_f32 v[106:107], v[114:115], v[68:69], v[66:67]
	ds_read_b128 v[66:69], v8 offset:7184
	ds_read_b32 v116, v9 offset:31744
	v_add_f32_e32 v106, v106, v107
	s_waitcnt lgkmcnt(11)
	v_pk_mul_f32 v[10:11], v[10:11], v[126:127]
	v_pk_mul_f32 v[122:123], v[18:19], v[124:125] op_sel_hi:[1,0]
	v_add_f32_dpp v18, v106, v106 quad_perm:[1,0,3,2] row_mask:0xf bank_mask:0xf bound_ctrl:1
	v_pk_fma_f32 v[10:11], v[128:129], v[12:13], v[10:11]
	v_pk_mul_f32 v[130:131], v[20:21], v[124:125] op_sel_hi:[1,0]
	v_add_f32_dpp v12, v18, v18 quad_perm:[2,3,0,1] row_mask:0xf bank_mask:0xf bound_ctrl:1
	v_pk_fma_f32 v[10:11], v[74:75], v[14:15], v[10:11]
	v_pk_mul_f32 v[132:133], v[22:23], v[124:125] op_sel_hi:[1,0]
	v_add_f32_dpp v12, v12, v12 row_half_mirror row_mask:0xf bank_mask:0xf bound_ctrl:1
	v_pk_fma_f32 v[10:11], v[114:115], v[16:17], v[10:11]
	v_pk_mul_f32 v[124:125], v[24:25], v[124:125] op_sel_hi:[1,0]
	v_cndmask_b32_e64 v101, v101, v12, s[52:53]
	v_add_f32_e32 v18, v10, v11
	ds_read_b128 v[10:13], v8 offset:40192
	ds_read_b128 v[14:17], v8 offset:40208
	v_add_f32_dpp v106, v18, v18 quad_perm:[1,0,3,2] row_mask:0xf bank_mask:0xf bound_ctrl:1
	ds_read_b128 v[18:21], v8 offset:15616
	ds_read_b128 v[22:25], v8 offset:15632
	v_add_f32_dpp v117, v106, v106 quad_perm:[2,3,0,1] row_mask:0xf bank_mask:0xf bound_ctrl:1
	ds_read_b128 v[106:109], v8 offset:48384
	ds_read_b128 v[110:113], v8 offset:48400
	v_add_f32_dpp v160, v117, v117 row_half_mirror row_mask:0xf bank_mask:0xf bound_ctrl:1
	v_pk_fma_f32 v[102:103], v[160:161], v[102:103], v[122:123] op_sel_hi:[0,1,1] neg_lo:[1,0,0] neg_hi:[1,0,0]
	v_pk_fma_f32 v[104:105], v[160:161], v[104:105], v[130:131] op_sel_hi:[0,1,1] neg_lo:[1,0,0] neg_hi:[1,0,0]
	v_pk_fma_f32 v[118:119], v[160:161], v[118:119], v[132:133] op_sel_hi:[0,1,1] neg_lo:[1,0,0] neg_hi:[1,0,0]
	v_pk_fma_f32 v[120:121], v[160:161], v[120:121], v[124:125] op_sel_hi:[0,1,1] neg_lo:[1,0,0] neg_hi:[1,0,0]
	v_pk_fma_f32 v[122:123], v[126:127], v[26:27], v[102:103]
	v_pk_fma_f32 v[124:125], v[128:129], v[28:29], v[104:105]
	v_pk_fma_f32 v[74:75], v[74:75], v[30:31], v[118:119]
	v_pk_fma_f32 v[118:119], v[114:115], v[32:33], v[120:121]
	v_pk_mul_f32 v[30:31], v[34:35], v[122:123]
	ds_read_b128 v[26:29], v8 offset:23808
	v_pk_fma_f32 v[34:35], v[124:125], v[36:37], v[30:31]
	ds_read_b128 v[30:33], v8 offset:23824
	v_pk_fma_f32 v[38:39], v[74:75], v[38:39], v[34:35]
	ds_read_b128 v[34:37], v8 offset:7424
	v_pk_fma_f32 v[102:103], v[118:119], v[40:41], v[38:39]
	ds_read_b128 v[38:41], v8 offset:7440
	ds_read_b32 v120, v9 offset:32000
	v_add_f32_e32 v102, v102, v103
	s_waitcnt lgkmcnt(11)
; #define LAS __attribute__((address_space(3)))
; #define SB_ __builtin_amdgcn_sched_barrier(0)
; __device__ __forceinline__ void scan_phase(const Args& a, int li, LAS unsigned char* lds) {
;     ...
;                 StepVec V0, V1, V2; SC_LOADV(V0, 0); SC_LOADV(V1, 1); float yk = 0.f, qprev = 0.f;
; #pragma unroll
;                 for (int t = 0; t < 32; ++t) {
;                     switch (t % 3) { case 0: SC_STEPF(V0, V2, (t + 2) & 31, (t + 7) & 7); break; case 1: SC_STEPF(V1, V0, (t + 2) & 31, (t + 7) & 7); break; default: SC_STEPF(V2, V1, (t + 2) & 31, (t + 7) & 7); break; }
;                     if ((t & 7) == 0 && t > 0) { *(LAS float*)(lds + SC_Y + (c & 1) * 4096 + ((t - 8) + cgp) * 128 + rl * 4) = yk; }
;                     SB_; }
	v_pk_mul_f32 v[0:1], v[0:1], v[122:123]
	v_pk_mul_f32 v[126:127], v[58:59], v[116:117] op_sel_hi:[1,0]
	v_add_f32_dpp v58, v102, v102 quad_perm:[1,0,3,2] row_mask:0xf bank_mask:0xf bound_ctrl:1
	v_pk_fma_f32 v[0:1], v[124:125], v[2:3], v[0:1]
	v_pk_mul_f32 v[128:129], v[60:61], v[116:117] op_sel_hi:[1,0]
	v_add_f32_dpp v2, v58, v58 quad_perm:[2,3,0,1] row_mask:0xf bank_mask:0xf bound_ctrl:1
	v_pk_fma_f32 v[0:1], v[74:75], v[4:5], v[0:1]
	v_pk_mul_f32 v[130:131], v[54:55], v[116:117] op_sel_hi:[1,0]
	v_add_f32_dpp v2, v2, v2 row_half_mirror row_mask:0xf bank_mask:0xf bound_ctrl:1
	v_pk_fma_f32 v[0:1], v[118:119], v[6:7], v[0:1]
	v_pk_mul_f32 v[132:133], v[56:57], v[116:117] op_sel_hi:[1,0]
	v_cndmask_b32_e64 v101, v101, v2, s[54:55]
	v_add_f32_e32 v54, v0, v1
	ds_read_b128 v[0:3], v8 offset:40448
	ds_read_b128 v[4:7], v8 offset:40464
	v_add_f32_dpp v102, v54, v54 quad_perm:[1,0,3,2] row_mask:0xf bank_mask:0xf bound_ctrl:1
	ds_read_b128 v[54:57], v8 offset:15872
	ds_read_b128 v[58:61], v8 offset:15888
	v_add_f32_dpp v121, v102, v102 quad_perm:[2,3,0,1] row_mask:0xf bank_mask:0xf bound_ctrl:1
	ds_read_b128 v[102:105], v8 offset:48640
	ds_read_b128 v[114:117], v8 offset:48656
	v_add_f32_dpp v160, v121, v121 row_half_mirror row_mask:0xf bank_mask:0xf bound_ctrl:1
	v_pk_fma_f32 v[50:51], v[160:161], v[50:51], v[126:127] op_sel_hi:[0,1,1] neg_lo:[1,0,0] neg_hi:[1,0,0]
	v_pk_fma_f32 v[52:53], v[160:161], v[52:53], v[128:129] op_sel_hi:[0,1,1] neg_lo:[1,0,0] neg_hi:[1,0,0]
	v_pk_fma_f32 v[70:71], v[160:161], v[70:71], v[130:131] op_sel_hi:[0,1,1] neg_lo:[1,0,0] neg_hi:[1,0,0]
	v_pk_fma_f32 v[72:73], v[160:161], v[72:73], v[132:133] op_sel_hi:[0,1,1] neg_lo:[1,0,0] neg_hi:[1,0,0]
	v_pk_fma_f32 v[122:123], v[122:123], v[42:43], v[50:51]
	v_pk_fma_f32 v[124:125], v[124:125], v[44:45], v[52:53]
	v_pk_fma_f32 v[74:75], v[74:75], v[46:47], v[70:71]
	v_pk_fma_f32 v[118:119], v[118:119], v[48:49], v[72:73]
	v_pk_mul_f32 v[46:47], v[62:63], v[122:123]
	ds_read_b128 v[42:45], v8 offset:24064
	v_pk_fma_f32 v[50:51], v[124:125], v[64:65], v[46:47]
	ds_read_b128 v[46:49], v8 offset:24080
	v_pk_fma_f32 v[62:63], v[74:75], v[66:67], v[50:51]
	ds_read_b128 v[50:53], v8 offset:7680
	v_pk_fma_f32 v[66:67], v[118:119], v[68:69], v[62:63]
	ds_read_b128 v[62:65], v8 offset:7696
	ds_read_b32 v126, v9 offset:32256
	v_add_f32_e32 v66, v66, v67
	s_waitcnt lgkmcnt(11)
	v_pk_mul_f32 v[10:11], v[10:11], v[122:123]
	v_pk_mul_f32 v[128:129], v[26:27], v[120:121] op_sel_hi:[1,0]
	v_add_f32_dpp v26, v66, v66 quad_perm:[1,0,3,2] row_mask:0xf bank_mask:0xf bound_ctrl:1
	v_pk_fma_f32 v[10:11], v[124:125], v[12:13], v[10:11]
	v_pk_mul_f32 v[130:131], v[28:29], v[120:121] op_sel_hi:[1,0]
	v_add_f32_dpp v12, v26, v26 quad_perm:[2,3,0,1] row_mask:0xf bank_mask:0xf bound_ctrl:1
	v_pk_fma_f32 v[10:11], v[74:75], v[14:15], v[10:11]
	v_pk_mul_f32 v[132:133], v[30:31], v[120:121] op_sel_hi:[1,0]
	v_add_f32_dpp v12, v12, v12 row_half_mirror row_mask:0xf bank_mask:0xf bound_ctrl:1
	v_pk_fma_f32 v[10:11], v[118:119], v[16:17], v[10:11]
	v_pk_mul_f32 v[120:121], v[32:33], v[120:121] op_sel_hi:[1,0]
	v_cndmask_b32_e64 v101, v101, v12, s[56:57]
	v_add_f32_e32 v26, v10, v11
	ds_read_b128 v[10:13], v8 offset:40704
	ds_read_b128 v[14:17], v8 offset:40720
	v_add_f32_dpp v66, v26, v26 quad_perm:[1,0,3,2] row_mask:0xf bank_mask:0xf bound_ctrl:1
	ds_read_b128 v[26:29], v8 offset:16128
	ds_read_b128 v[30:33], v8 offset:16144
	v_add_f32_dpp v127, v66, v66 quad_perm:[2,3,0,1] row_mask:0xf bank_mask:0xf bound_ctrl:1
	ds_read_b128 v[66:69], v8 offset:48896
	ds_read_b128 v[70:73], v8 offset:48912
	v_add_f32_dpp v160, v127, v127 row_half_mirror row_mask:0xf bank_mask:0xf bound_ctrl:1
	v_pk_fma_f32 v[106:107], v[160:161], v[106:107], v[128:129] op_sel_hi:[0,1,1] neg_lo:[1,0,0] neg_hi:[1,0,0]
	v_pk_fma_f32 v[108:109], v[160:161], v[108:109], v[130:131] op_sel_hi:[0,1,1] neg_lo:[1,0,0] neg_hi:[1,0,0]
	v_pk_fma_f32 v[110:111], v[160:161], v[110:111], v[132:133] op_sel_hi:[0,1,1] neg_lo:[1,0,0] neg_hi:[1,0,0]
	v_pk_fma_f32 v[112:113], v[160:161], v[112:113], v[120:121] op_sel_hi:[0,1,1] neg_lo:[1,0,0] neg_hi:[1,0,0]
	v_pk_fma_f32 v[106:107], v[122:123], v[18:19], v[106:107]
	v_pk_fma_f32 v[108:109], v[124:125], v[20:21], v[108:109]
	v_pk_fma_f32 v[74:75], v[74:75], v[22:23], v[110:111]
	v_pk_fma_f32 v[110:111], v[118:119], v[24:25], v[112:113]
	v_pk_mul_f32 v[22:23], v[34:35], v[106:107]
	ds_read_b128 v[18:21], v8 offset:24320
	v_pk_fma_f32 v[34:35], v[108:109], v[36:37], v[22:23]
	ds_read_b128 v[22:25], v8 offset:24336
	v_pk_fma_f32 v[38:39], v[74:75], v[38:39], v[34:35]
	ds_read_b128 v[34:37], v8 offset:7936
	v_pk_fma_f32 v[112:113], v[110:111], v[40:41], v[38:39]
	ds_read_b128 v[38:41], v8 offset:7952
	ds_read_b32 v8, v9 offset:32512
	v_add_f32_e32 v9, v112, v113
	s_waitcnt lgkmcnt(11)
; #define LAS __attribute__((address_space(3)))
; __device__ __forceinline__ float sum8(float x)  { x += dppf<0xB1>(x); x += dppf<0x4E>(x); x += dppf<0x141>(x); return x; }
; #define SB_ __builtin_amdgcn_sched_barrier(0)
; __device__ __forceinline__ void scan_phase(const Args& a, int li, LAS unsigned char* lds) {
;     ...
;                 StepVec V0, V1, V2; SC_LOADV(V0, 0); SC_LOADV(V1, 1); float yk = 0.f, qprev = 0.f;
; #pragma unroll
;                 for (int t = 0; t < 32; ++t) {
;                     switch (t % 3) { case 0: SC_STEPF(V0, V2, (t + 2) & 31, (t + 7) & 7); break; case 1: SC_STEPF(V1, V0, (t + 2) & 31, (t + 7) & 7); break; default: SC_STEPF(V2, V1, (t + 2) & 31, (t + 7) & 7); break; }
;                     if ((t & 7) == 0 && t > 0) { *(LAS float*)(lds + SC_Y + (c & 1) * 4096 + ((t - 8) + cgp) * 128 + rl * 4) = yk; }
;                     SB_; }
;                 { const float y31 = sum8(qprev); yk = (cgp == 7) ? y31 : yk; *(LAS float*)(lds + SC_Y + (c & 1) * 4096 + (24 + cgp) * 128 + rl * 4) = yk; }
;                 __syncthreads();
	v_pk_mul_f32 v[0:1], v[0:1], v[106:107]
	v_pk_mul_f32 v[42:43], v[42:43], v[126:127] op_sel_hi:[1,0]
	v_add_f32_dpp v9, v9, v9 quad_perm:[1,0,3,2] row_mask:0xf bank_mask:0xf bound_ctrl:1
	v_pk_fma_f32 v[0:1], v[108:109], v[2:3], v[0:1]
	v_pk_mul_f32 v[2:3], v[44:45], v[126:127] op_sel_hi:[1,0]
	v_add_f32_dpp v9, v9, v9 quad_perm:[2,3,0,1] row_mask:0xf bank_mask:0xf bound_ctrl:1
	v_pk_fma_f32 v[0:1], v[74:75], v[4:5], v[0:1]
	v_pk_mul_f32 v[4:5], v[46:47], v[126:127] op_sel_hi:[1,0]
	v_add_f32_dpp v9, v9, v9 row_half_mirror row_mask:0xf bank_mask:0xf bound_ctrl:1
	v_pk_fma_f32 v[0:1], v[110:111], v[6:7], v[0:1]
	v_pk_mul_f32 v[6:7], v[48:49], v[126:127] op_sel_hi:[1,0]
	v_cndmask_b32_e64 v44, v101, v9, s[58:59]
	v_add_f32_e32 v0, v0, v1
	s_nop 1
	v_add_f32_dpp v0, v0, v0 quad_perm:[1,0,3,2] row_mask:0xf bank_mask:0xf bound_ctrl:1
	s_nop 1
	v_add_f32_dpp v0, v0, v0 quad_perm:[2,3,0,1] row_mask:0xf bank_mask:0xf bound_ctrl:1
	s_nop 1
	v_add_f32_dpp v0, v0, v0 row_half_mirror row_mask:0xf bank_mask:0xf bound_ctrl:1
	v_pk_fma_f32 v[42:43], v[0:1], v[102:103], v[42:43] op_sel_hi:[0,1,1] neg_lo:[1,0,0] neg_hi:[1,0,0]
	v_pk_fma_f32 v[2:3], v[0:1], v[104:105], v[2:3] op_sel_hi:[0,1,1] neg_lo:[1,0,0] neg_hi:[1,0,0]
	v_pk_fma_f32 v[4:5], v[0:1], v[114:115], v[4:5] op_sel_hi:[0,1,1] neg_lo:[1,0,0] neg_hi:[1,0,0]
	v_pk_fma_f32 v[0:1], v[0:1], v[116:117], v[6:7] op_sel_hi:[0,1,1] neg_lo:[1,0,0] neg_hi:[1,0,0]
	v_pk_fma_f32 v[6:7], v[106:107], v[54:55], v[42:43]
	v_pk_fma_f32 v[2:3], v[108:109], v[56:57], v[2:3]
	v_pk_fma_f32 v[4:5], v[74:75], v[58:59], v[4:5]
	v_pk_fma_f32 v[42:43], v[110:111], v[60:61], v[0:1]
	v_pk_mul_f32 v[0:1], v[50:51], v[6:7]
	s_nop 0
	v_pk_fma_f32 v[0:1], v[2:3], v[52:53], v[0:1]
	s_nop 0
	v_pk_fma_f32 v[0:1], v[4:5], v[62:63], v[0:1]
	s_nop 0
	v_pk_fma_f32 v[0:1], v[42:43], v[64:65], v[0:1]
	s_nop 0
	v_add_f32_e32 v9, v0, v1
	s_waitcnt lgkmcnt(0)
	v_pk_mul_f32 v[0:1], v[10:11], v[6:7]
	v_pk_mul_f32 v[10:11], v[18:19], v[8:9] op_sel_hi:[1,0]
	v_add_f32_dpp v9, v9, v9 quad_perm:[1,0,3,2] row_mask:0xf bank_mask:0xf bound_ctrl:1
	v_pk_fma_f32 v[0:1], v[2:3], v[12:13], v[0:1]
	v_pk_mul_f32 v[12:13], v[20:21], v[8:9] op_sel_hi:[1,0]
	v_add_f32_dpp v9, v9, v9 quad_perm:[2,3,0,1] row_mask:0xf bank_mask:0xf bound_ctrl:1
	v_pk_fma_f32 v[0:1], v[4:5], v[14:15], v[0:1]
	v_pk_mul_f32 v[14:15], v[22:23], v[8:9] op_sel_hi:[1,0]
	v_add_f32_dpp v18, v9, v9 row_half_mirror row_mask:0xf bank_mask:0xf bound_ctrl:1
	v_pk_fma_f32 v[0:1], v[42:43], v[16:17], v[0:1]
	v_pk_mul_f32 v[8:9], v[24:25], v[8:9] op_sel_hi:[1,0]
	v_cndmask_b32_e64 v16, v44, v18, s[60:61]
	v_add_f32_e32 v0, v0, v1
	s_nop 1
	v_add_f32_dpp v0, v0, v0 quad_perm:[1,0,3,2] row_mask:0xf bank_mask:0xf bound_ctrl:1
	s_nop 1
	v_add_f32_dpp v0, v0, v0 quad_perm:[2,3,0,1] row_mask:0xf bank_mask:0xf bound_ctrl:1
	s_nop 1
	v_add_f32_dpp v0, v0, v0 row_half_mirror row_mask:0xf bank_mask:0xf bound_ctrl:1
	v_pk_fma_f32 v[10:11], v[0:1], v[66:67], v[10:11] op_sel_hi:[0,1,1] neg_lo:[1,0,0] neg_hi:[1,0,0]
	v_pk_fma_f32 v[12:13], v[0:1], v[68:69], v[12:13] op_sel_hi:[0,1,1] neg_lo:[1,0,0] neg_hi:[1,0,0]
	v_pk_fma_f32 v[14:15], v[0:1], v[70:71], v[14:15] op_sel_hi:[0,1,1] neg_lo:[1,0,0] neg_hi:[1,0,0]
	v_pk_fma_f32 v[8:9], v[0:1], v[72:73], v[8:9] op_sel_hi:[0,1,1] neg_lo:[1,0,0] neg_hi:[1,0,0]
	v_pk_fma_f32 v[0:1], v[6:7], v[26:27], v[10:11]
	v_pk_fma_f32 v[2:3], v[2:3], v[28:29], v[12:13]
	v_pk_fma_f32 v[4:5], v[4:5], v[30:31], v[14:15]
	v_pk_fma_f32 v[6:7], v[42:43], v[32:33], v[8:9]
	v_pk_mul_f32 v[8:9], v[34:35], v[0:1]
	s_nop 0
	v_pk_fma_f32 v[8:9], v[2:3], v[36:37], v[8:9]
	s_nop 0
	v_pk_fma_f32 v[8:9], v[4:5], v[38:39], v[8:9]
	s_nop 0
	v_pk_fma_f32 v[8:9], v[6:7], v[40:41], v[8:9]
	s_nop 0
	v_add_f32_e32 v8, v8, v9
	s_nop 1
	v_add_f32_dpp v8, v8, v8 quad_perm:[1,0,3,2] row_mask:0xf bank_mask:0xf bound_ctrl:1
	s_add_i32 s1, s1, 1
	v_add_u32_e32 v9, s4, v147
	v_add_f32_dpp v8, v8, v8 quad_perm:[2,3,0,1] row_mask:0xf bank_mask:0xf bound_ctrl:1
	s_cmpk_lg_i32 s1, 0x80
	s_nop 0
	v_add_f32_dpp v8, v8, v8 row_half_mirror row_mask:0xf bank_mask:0xf bound_ctrl:1
	v_cndmask_b32_e64 v8, v16, v8, s[38:39]
	ds_write_b32 v9, v8 offset:3072
	s_waitcnt lgkmcnt(0)
	s_barrier
	s_cbranch_scc1 .LBB0_532
	s_mov_b64 s[0:1], 0
